# nt hint also on the read-once f32 weight loads of phase 0 (adaLN w_ada, early+late transposes)
# speedup vs baseline: 1.0254x; 1.0056x over previous
.LBB0_26:
	s_mov_b64 s[12:13], 0x60000
	v_add_co_u32_e32 v244, vcc, 0xffd60000, v6
	s_nop 1
	v_addc_co_u32_e32 v245, vcc, -1, v7, vcc
	global_load_dword v178, v[244:245], off nt
	v_lshl_add_u64 v[244:245], v[244:245], 0, s[12:13]
	global_load_dword v179, v[244:245], off nt
	v_lshl_add_u64 v[244:245], v[244:245], 0, s[12:13]
	global_load_dword v180, v[244:245], off nt
	v_lshl_add_u64 v[244:245], v[244:245], 0, s[12:13]
	global_load_dword v181, v[244:245], off nt
	v_lshl_add_u64 v[244:245], v[244:245], 0, s[12:13]
	global_load_dword v182, v[244:245], off nt
	v_lshl_add_u64 v[244:245], v[244:245], 0, s[12:13]
	global_load_dword v183, v[244:245], off nt
	v_lshl_add_u64 v[244:245], v[244:245], 0, s[12:13]
	global_load_dword v184, v[244:245], off nt
	v_lshl_add_u64 v[244:245], v[244:245], 0, s[12:13]
	global_load_dword v185, v[244:245], off nt
	v_lshl_add_u64 v[244:245], v[244:245], 0, s[12:13]
	global_load_dword v186, v[244:245], off nt
	v_lshl_add_u64 v[244:245], v[244:245], 0, s[12:13]
	global_load_dword v187, v[244:245], off nt
	v_lshl_add_u64 v[244:245], v[244:245], 0, s[12:13]
	global_load_dword v188, v[244:245], off nt
	v_lshl_add_u64 v[244:245], v[244:245], 0, s[12:13]
	global_load_dword v189, v[244:245], off nt
	v_lshl_add_u64 v[244:245], v[244:245], 0, s[12:13]
	global_load_dword v190, v[244:245], off nt
	v_lshl_add_u64 v[244:245], v[244:245], 0, s[12:13]
	global_load_dword v191, v[244:245], off nt
	v_lshl_add_u64 v[244:245], v[244:245], 0, s[12:13]
	global_load_dword v192, v[244:245], off nt
	v_lshl_add_u64 v[244:245], v[244:245], 0, s[12:13]
	global_load_dword v193, v[244:245], off nt
	v_lshl_add_u64 v[244:245], v[244:245], 0, s[12:13]
	global_load_dword v194, v[244:245], off nt
	v_lshl_add_u64 v[244:245], v[244:245], 0, s[12:13]
	global_load_dword v195, v[244:245], off nt
	v_lshl_add_u64 v[244:245], v[244:245], 0, s[12:13]
	global_load_dword v196, v[244:245], off nt
	v_lshl_add_u64 v[244:245], v[244:245], 0, s[12:13]
	global_load_dword v197, v[244:245], off nt
	v_lshl_add_u64 v[244:245], v[244:245], 0, s[12:13]
	global_load_dword v198, v[244:245], off nt
	v_lshl_add_u64 v[244:245], v[244:245], 0, s[12:13]
	global_load_dword v199, v[244:245], off nt
	v_lshl_add_u64 v[244:245], v[244:245], 0, s[12:13]
	global_load_dword v200, v[244:245], off nt
	v_lshl_add_u64 v[244:245], v[244:245], 0, s[12:13]
	global_load_dword v201, v[244:245], off nt
	v_lshl_add_u64 v[244:245], v[244:245], 0, s[12:13]
	global_load_dword v204, v[244:245], off nt
	v_lshl_add_u64 v[244:245], v[244:245], 0, s[12:13]
	global_load_dword v205, v[244:245], off nt
	v_lshl_add_u64 v[244:245], v[244:245], 0, s[12:13]
	global_load_dword v206, v[244:245], off nt
	v_lshl_add_u64 v[244:245], v[244:245], 0, s[12:13]
	global_load_dword v207, v[244:245], off nt
	v_lshl_add_u64 v[244:245], v[244:245], 0, s[12:13]
	global_load_dword v208, v[244:245], off nt
	v_lshl_add_u64 v[244:245], v[244:245], 0, s[12:13]
	global_load_dword v209, v[244:245], off nt
	v_lshl_add_u64 v[244:245], v[244:245], 0, s[12:13]
	global_load_dword v210, v[244:245], off nt
	v_lshl_add_u64 v[244:245], v[244:245], 0, s[12:13]
	global_load_dword v211, v[244:245], off nt
	v_lshl_add_u64 v[244:245], v[244:245], 0, s[12:13]
	global_load_dword v212, v[244:245], off nt
	v_lshl_add_u64 v[244:245], v[244:245], 0, s[12:13]
	global_load_dword v213, v[244:245], off nt
	v_lshl_add_u64 v[244:245], v[244:245], 0, s[12:13]
	global_load_dword v214, v[244:245], off nt
	v_lshl_add_u64 v[244:245], v[244:245], 0, s[12:13]
	global_load_dword v215, v[244:245], off nt
	v_lshl_add_u64 v[244:245], v[244:245], 0, s[12:13]
	global_load_dword v216, v[244:245], off nt
	v_lshl_add_u64 v[244:245], v[244:245], 0, s[12:13]
	global_load_dword v217, v[244:245], off nt
	v_lshl_add_u64 v[244:245], v[244:245], 0, s[12:13]
	global_load_dword v218, v[244:245], off nt
	v_lshl_add_u64 v[244:245], v[244:245], 0, s[12:13]
	global_load_dword v219, v[244:245], off nt
	v_lshl_add_u64 v[244:245], v[244:245], 0, s[12:13]
	global_load_dword v220, v[244:245], off nt
	v_lshl_add_u64 v[244:245], v[244:245], 0, s[12:13]
	global_load_dword v221, v[244:245], off nt
	v_lshl_add_u64 v[244:245], v[244:245], 0, s[12:13]
	global_load_dword v222, v[244:245], off nt
	v_lshl_add_u64 v[244:245], v[244:245], 0, s[12:13]
	global_load_dword v223, v[244:245], off nt
	v_lshl_add_u64 v[244:245], v[244:245], 0, s[12:13]
	global_load_dword v224, v[244:245], off nt
	v_lshl_add_u64 v[244:245], v[244:245], 0, s[12:13]
	global_load_dword v225, v[244:245], off nt
	v_lshl_add_u64 v[244:245], v[244:245], 0, s[12:13]
	global_load_dword v226, v[244:245], off nt
	v_lshl_add_u64 v[244:245], v[244:245], 0, s[12:13]
	global_load_dword v227, v[244:245], off nt
	v_lshl_add_u64 v[244:245], v[244:245], 0, s[12:13]
	global_load_dword v228, v[244:245], off nt
	v_lshl_add_u64 v[244:245], v[244:245], 0, s[12:13]
	global_load_dword v229, v[244:245], off nt
	v_lshl_add_u64 v[244:245], v[244:245], 0, s[12:13]
	global_load_dword v230, v[244:245], off nt
	v_lshl_add_u64 v[244:245], v[244:245], 0, s[12:13]
	global_load_dword v231, v[244:245], off nt
	v_lshl_add_u64 v[244:245], v[244:245], 0, s[12:13]
	global_load_dword v232, v[244:245], off nt
	v_lshl_add_u64 v[244:245], v[244:245], 0, s[12:13]
	global_load_dword v233, v[244:245], off nt
	v_lshl_add_u64 v[244:245], v[244:245], 0, s[12:13]
	global_load_dword v234, v[244:245], off nt
	v_lshl_add_u64 v[244:245], v[244:245], 0, s[12:13]
	global_load_dword v235, v[244:245], off nt
	v_lshl_add_u64 v[244:245], v[244:245], 0, s[12:13]
	global_load_dword v236, v[244:245], off nt
	v_lshl_add_u64 v[244:245], v[244:245], 0, s[12:13]
	global_load_dword v237, v[244:245], off nt
	v_lshl_add_u64 v[244:245], v[244:245], 0, s[12:13]
	global_load_dword v238, v[244:245], off nt
	v_lshl_add_u64 v[244:245], v[244:245], 0, s[12:13]
	global_load_dword v239, v[244:245], off nt
	v_lshl_add_u64 v[244:245], v[244:245], 0, s[12:13]
	global_load_dword v240, v[244:245], off nt
	v_lshl_add_u64 v[244:245], v[244:245], 0, s[12:13]
	global_load_dword v241, v[244:245], off nt
	v_lshl_add_u64 v[244:245], v[244:245], 0, s[12:13]
	global_load_dword v242, v[244:245], off nt
	v_lshl_add_u64 v[244:245], v[244:245], 0, s[12:13]
	global_load_dword v243, v[244:245], off nt
	ds_read2_b32 v[20:21], v18 offset1:16
	v_add_u32_e32 v54, 0x1000, v18
	v_add_u32_e32 v62, 0x4000, v18
	s_waitcnt lgkmcnt(0)
	v_mov_b32_e32 v64, v20
	ds_read2_b32 v[26:27], v18 offset0:32 offset1:48
	ds_read2_b32 v[28:29], v18 offset0:64 offset1:80
	ds_read2_b32 v[30:31], v18 offset0:96 offset1:112
	v_add_u32_e32 v17, 0x2000, v18
	v_add_u32_e32 v23, 0x3000, v18
	ds_read2_b32 v[32:33], v54 offset1:16
	ds_read2_b32 v[34:35], v17 offset1:16
	ds_read2_b32 v[36:37], v23 offset1:16
	ds_read2_b32 v[38:39], v62 offset1:16
	ds_read2_b32 v[40:41], v54 offset0:32 offset1:48
	ds_read2_b32 v[42:43], v17 offset0:32 offset1:48
	ds_read2_b32 v[44:45], v23 offset0:32 offset1:48
	ds_read2_b32 v[46:47], v62 offset0:32 offset1:48
	ds_read2_b32 v[48:49], v54 offset0:64 offset1:80
	ds_read2_b32 v[50:51], v17 offset0:64 offset1:80
	ds_read2_b32 v[52:53], v23 offset0:64 offset1:80
	ds_read2_b32 v[54:55], v54 offset0:96 offset1:112
	ds_read2_b32 v[56:57], v17 offset0:96 offset1:112
	ds_read2_b32 v[58:59], v23 offset0:96 offset1:112
	ds_read2_b32 v[60:61], v62 offset0:64 offset1:80
	ds_read2_b32 v[62:63], v62 offset0:96 offset1:112
	s_waitcnt lgkmcnt(14)
	v_mov_b32_e32 v20, v26
	v_mov_b32_e32 v26, v28
	v_mov_b32_e32 v28, v30
	v_mov_b32_e32 v65, v32
	v_mov_b32_e32 v32, v21
	s_waitcnt lgkmcnt(11)
	v_mov_b32_e32 v21, v40
	v_mov_b32_e32 v40, v27
	s_waitcnt lgkmcnt(7)
	v_mov_b32_e32 v27, v48
	v_mov_b32_e32 v48, v29
	s_waitcnt lgkmcnt(4)
	v_mov_b32_e32 v29, v54
	v_mov_b32_e32 v54, v31
	v_mov_b32_e32 v30, v34
	v_mov_b32_e32 v31, v36
	v_mov_b32_e32 v36, v35
	v_mov_b32_e32 v34, v42
	v_mov_b32_e32 v42, v50
	s_waitcnt lgkmcnt(3)
	v_mov_b32_e32 v50, v56
	v_mov_b32_e32 v35, v44
	v_mov_b32_e32 v44, v43
	v_mov_b32_e32 v43, v52
	v_mov_b32_e32 v52, v51
	s_waitcnt lgkmcnt(2)
	v_mov_b32_e32 v51, v58
	v_mov_b32_e32 v58, v57
	v_add_u32_e32 v18, 0x200, v18
	s_waitcnt vmcnt(56)
	v_mov_b32_e32 v12, v178
	v_mov_b32_e32 v13, v179
	v_mov_b32_e32 v14, v180
	v_mov_b32_e32 v15, v181
	v_mov_b32_e32 v24, v182
	v_mov_b32_e32 v25, v183
	v_mov_b32_e32 v16, v184
	v_mov_b32_e32 v22, v185
	v_pk_fma_f32 v[10:11], v[12:13], v[64:65], v[10:11] op_sel_hi:[0,1,1]
	v_mov_b32_e32 v56, v13
	v_pk_fma_f32 v[8:9], v[12:13], v[30:31], v[8:9] op_sel_hi:[0,1,1]
	v_pk_mul_f32 v[38:39], v[12:13], v[38:39]
	v_pk_fma_f32 v[10:11], v[56:57], v[32:33], v[10:11] op_sel_hi:[0,1,1]
	v_pk_fma_f32 v[8:9], v[56:57], v[36:37], v[8:9] op_sel_hi:[0,1,1]
	v_add_f32_e32 v5, v5, v38
	v_add_f32_e32 v5, v5, v39
	v_pk_fma_f32 v[10:11], v[14:15], v[20:21], v[10:11] op_sel_hi:[0,1,1]
	v_mov_b32_e32 v20, v15
	v_pk_fma_f32 v[8:9], v[14:15], v[34:35], v[8:9] op_sel_hi:[0,1,1]
	v_pk_mul_f32 v[12:13], v[14:15], v[46:47]
	v_pk_fma_f32 v[10:11], v[20:21], v[40:41], v[10:11] op_sel_hi:[0,1,1]
	v_pk_fma_f32 v[8:9], v[20:21], v[44:45], v[8:9] op_sel_hi:[0,1,1]
	v_add_f32_e32 v5, v5, v12
	v_add_f32_e32 v5, v5, v13
	v_pk_fma_f32 v[10:11], v[24:25], v[26:27], v[10:11] op_sel_hi:[0,1,1]
	v_mov_b32_e32 v14, v25
	v_pk_fma_f32 v[8:9], v[24:25], v[42:43], v[8:9] op_sel_hi:[0,1,1]
	s_waitcnt lgkmcnt(1)
	v_pk_mul_f32 v[12:13], v[24:25], v[60:61]
	v_pk_fma_f32 v[10:11], v[14:15], v[48:49], v[10:11] op_sel_hi:[0,1,1]
	v_pk_fma_f32 v[8:9], v[14:15], v[52:53], v[8:9] op_sel_hi:[0,1,1]
	v_add_f32_e32 v5, v5, v12
	v_pk_fma_f32 v[10:11], v[16:17], v[28:29], v[10:11] op_sel_hi:[0,1,1]
	v_pk_fma_f32 v[8:9], v[16:17], v[50:51], v[8:9] op_sel_hi:[0,1,1]
	v_mov_b32_e32 v17, v22
	v_add_f32_e32 v5, v5, v13
	s_waitcnt lgkmcnt(0)
	v_pk_mul_f32 v[12:13], v[16:17], v[62:63]
	v_pk_fma_f32 v[10:11], v[22:23], v[54:55], v[10:11] op_sel_hi:[0,1,1]
	v_add_f32_e32 v5, v5, v12
	v_pk_fma_f32 v[8:9], v[22:23], v[58:59], v[8:9] op_sel_hi:[0,1,1]
	v_add_f32_e32 v5, v5, v13
	ds_read2_b32 v[20:21], v18 offset1:16
	v_add_u32_e32 v54, 0x1000, v18
	v_add_u32_e32 v62, 0x4000, v18
	s_waitcnt lgkmcnt(0)
	v_mov_b32_e32 v64, v20
	ds_read2_b32 v[26:27], v18 offset0:32 offset1:48
	ds_read2_b32 v[28:29], v18 offset0:64 offset1:80
	ds_read2_b32 v[30:31], v18 offset0:96 offset1:112
	v_add_u32_e32 v17, 0x2000, v18
	v_add_u32_e32 v23, 0x3000, v18
	ds_read2_b32 v[32:33], v54 offset1:16
	ds_read2_b32 v[34:35], v17 offset1:16
	ds_read2_b32 v[36:37], v23 offset1:16
	ds_read2_b32 v[38:39], v62 offset1:16
	ds_read2_b32 v[40:41], v54 offset0:32 offset1:48
	ds_read2_b32 v[42:43], v17 offset0:32 offset1:48
	ds_read2_b32 v[44:45], v23 offset0:32 offset1:48
	ds_read2_b32 v[46:47], v62 offset0:32 offset1:48
	ds_read2_b32 v[48:49], v54 offset0:64 offset1:80
	ds_read2_b32 v[50:51], v17 offset0:64 offset1:80
	ds_read2_b32 v[52:53], v23 offset0:64 offset1:80
	ds_read2_b32 v[54:55], v54 offset0:96 offset1:112
	ds_read2_b32 v[56:57], v17 offset0:96 offset1:112
	ds_read2_b32 v[58:59], v23 offset0:96 offset1:112
	ds_read2_b32 v[60:61], v62 offset0:64 offset1:80
	ds_read2_b32 v[62:63], v62 offset0:96 offset1:112
	s_waitcnt lgkmcnt(14)
	v_mov_b32_e32 v20, v26
	v_mov_b32_e32 v26, v28
	v_mov_b32_e32 v28, v30
	v_mov_b32_e32 v65, v32
	v_mov_b32_e32 v32, v21
	s_waitcnt lgkmcnt(11)
	v_mov_b32_e32 v21, v40
	v_mov_b32_e32 v40, v27
	s_waitcnt lgkmcnt(7)
	v_mov_b32_e32 v27, v48
	v_mov_b32_e32 v48, v29
	s_waitcnt lgkmcnt(4)
	v_mov_b32_e32 v29, v54
	v_mov_b32_e32 v54, v31
	v_mov_b32_e32 v30, v34
	v_mov_b32_e32 v31, v36
	v_mov_b32_e32 v36, v35
	v_mov_b32_e32 v34, v42
	v_mov_b32_e32 v42, v50
	s_waitcnt lgkmcnt(3)
	v_mov_b32_e32 v50, v56
	v_mov_b32_e32 v35, v44
	v_mov_b32_e32 v44, v43
	v_mov_b32_e32 v43, v52
	v_mov_b32_e32 v52, v51
	s_waitcnt lgkmcnt(2)
	v_mov_b32_e32 v51, v58
	v_mov_b32_e32 v58, v57
	v_add_u32_e32 v18, 0x200, v18
	s_waitcnt vmcnt(48)
	v_mov_b32_e32 v12, v186
	v_mov_b32_e32 v13, v187
	v_mov_b32_e32 v14, v188
	v_mov_b32_e32 v15, v189
	v_mov_b32_e32 v24, v190
	v_mov_b32_e32 v25, v191
	v_mov_b32_e32 v16, v192
	v_mov_b32_e32 v22, v193
	v_pk_fma_f32 v[10:11], v[12:13], v[64:65], v[10:11] op_sel_hi:[0,1,1]
	v_mov_b32_e32 v56, v13
	v_pk_fma_f32 v[8:9], v[12:13], v[30:31], v[8:9] op_sel_hi:[0,1,1]
	v_pk_mul_f32 v[38:39], v[12:13], v[38:39]
	v_pk_fma_f32 v[10:11], v[56:57], v[32:33], v[10:11] op_sel_hi:[0,1,1]
	v_pk_fma_f32 v[8:9], v[56:57], v[36:37], v[8:9] op_sel_hi:[0,1,1]
	v_add_f32_e32 v5, v5, v38
	v_add_f32_e32 v5, v5, v39
	v_pk_fma_f32 v[10:11], v[14:15], v[20:21], v[10:11] op_sel_hi:[0,1,1]
	v_mov_b32_e32 v20, v15
	v_pk_fma_f32 v[8:9], v[14:15], v[34:35], v[8:9] op_sel_hi:[0,1,1]
	v_pk_mul_f32 v[12:13], v[14:15], v[46:47]
	v_pk_fma_f32 v[10:11], v[20:21], v[40:41], v[10:11] op_sel_hi:[0,1,1]
	v_pk_fma_f32 v[8:9], v[20:21], v[44:45], v[8:9] op_sel_hi:[0,1,1]
	v_add_f32_e32 v5, v5, v12
	v_add_f32_e32 v5, v5, v13
	v_pk_fma_f32 v[10:11], v[24:25], v[26:27], v[10:11] op_sel_hi:[0,1,1]
	v_mov_b32_e32 v14, v25
	v_pk_fma_f32 v[8:9], v[24:25], v[42:43], v[8:9] op_sel_hi:[0,1,1]
	s_waitcnt lgkmcnt(1)
	v_pk_mul_f32 v[12:13], v[24:25], v[60:61]
	v_pk_fma_f32 v[10:11], v[14:15], v[48:49], v[10:11] op_sel_hi:[0,1,1]
	v_pk_fma_f32 v[8:9], v[14:15], v[52:53], v[8:9] op_sel_hi:[0,1,1]
	v_add_f32_e32 v5, v5, v12
	v_pk_fma_f32 v[10:11], v[16:17], v[28:29], v[10:11] op_sel_hi:[0,1,1]
	v_pk_fma_f32 v[8:9], v[16:17], v[50:51], v[8:9] op_sel_hi:[0,1,1]
	v_mov_b32_e32 v17, v22
	v_add_f32_e32 v5, v5, v13
	s_waitcnt lgkmcnt(0)
	v_pk_mul_f32 v[12:13], v[16:17], v[62:63]
	v_pk_fma_f32 v[10:11], v[22:23], v[54:55], v[10:11] op_sel_hi:[0,1,1]
	v_add_f32_e32 v5, v5, v12
	v_pk_fma_f32 v[8:9], v[22:23], v[58:59], v[8:9] op_sel_hi:[0,1,1]
	v_add_f32_e32 v5, v5, v13
	ds_read2_b32 v[20:21], v18 offset1:16
	v_add_u32_e32 v54, 0x1000, v18
	v_add_u32_e32 v62, 0x4000, v18
	s_waitcnt lgkmcnt(0)
	v_mov_b32_e32 v64, v20
	ds_read2_b32 v[26:27], v18 offset0:32 offset1:48
	ds_read2_b32 v[28:29], v18 offset0:64 offset1:80
	ds_read2_b32 v[30:31], v18 offset0:96 offset1:112
	v_add_u32_e32 v17, 0x2000, v18
	v_add_u32_e32 v23, 0x3000, v18
	ds_read2_b32 v[32:33], v54 offset1:16
	ds_read2_b32 v[34:35], v17 offset1:16
	ds_read2_b32 v[36:37], v23 offset1:16
	ds_read2_b32 v[38:39], v62 offset1:16
	ds_read2_b32 v[40:41], v54 offset0:32 offset1:48
	ds_read2_b32 v[42:43], v17 offset0:32 offset1:48
	ds_read2_b32 v[44:45], v23 offset0:32 offset1:48
	ds_read2_b32 v[46:47], v62 offset0:32 offset1:48
	ds_read2_b32 v[48:49], v54 offset0:64 offset1:80
	ds_read2_b32 v[50:51], v17 offset0:64 offset1:80
	ds_read2_b32 v[52:53], v23 offset0:64 offset1:80
	ds_read2_b32 v[54:55], v54 offset0:96 offset1:112
	ds_read2_b32 v[56:57], v17 offset0:96 offset1:112
	ds_read2_b32 v[58:59], v23 offset0:96 offset1:112
	ds_read2_b32 v[60:61], v62 offset0:64 offset1:80
	ds_read2_b32 v[62:63], v62 offset0:96 offset1:112
	s_waitcnt lgkmcnt(14)
	v_mov_b32_e32 v20, v26
	v_mov_b32_e32 v26, v28
	v_mov_b32_e32 v28, v30
	v_mov_b32_e32 v65, v32
	v_mov_b32_e32 v32, v21
	s_waitcnt lgkmcnt(11)
	v_mov_b32_e32 v21, v40
	v_mov_b32_e32 v40, v27
	s_waitcnt lgkmcnt(7)
	v_mov_b32_e32 v27, v48
	v_mov_b32_e32 v48, v29
	s_waitcnt lgkmcnt(4)
	v_mov_b32_e32 v29, v54
	v_mov_b32_e32 v54, v31
	v_mov_b32_e32 v30, v34
	v_mov_b32_e32 v31, v36
	v_mov_b32_e32 v36, v35
	v_mov_b32_e32 v34, v42
	v_mov_b32_e32 v42, v50
	s_waitcnt lgkmcnt(3)
	v_mov_b32_e32 v50, v56
	v_mov_b32_e32 v35, v44
	v_mov_b32_e32 v44, v43
	v_mov_b32_e32 v43, v52
	v_mov_b32_e32 v52, v51
	s_waitcnt lgkmcnt(2)
	v_mov_b32_e32 v51, v58
	v_mov_b32_e32 v58, v57
	v_add_u32_e32 v18, 0x200, v18
	s_waitcnt vmcnt(40)
	v_mov_b32_e32 v12, v194
	v_mov_b32_e32 v13, v195
	v_mov_b32_e32 v14, v196
	v_mov_b32_e32 v15, v197
	v_mov_b32_e32 v24, v198
	v_mov_b32_e32 v25, v199
	v_mov_b32_e32 v16, v200
	v_mov_b32_e32 v22, v201
	v_pk_fma_f32 v[10:11], v[12:13], v[64:65], v[10:11] op_sel_hi:[0,1,1]
	v_mov_b32_e32 v56, v13
	v_pk_fma_f32 v[8:9], v[12:13], v[30:31], v[8:9] op_sel_hi:[0,1,1]
	v_pk_mul_f32 v[38:39], v[12:13], v[38:39]
	v_pk_fma_f32 v[10:11], v[56:57], v[32:33], v[10:11] op_sel_hi:[0,1,1]
	v_pk_fma_f32 v[8:9], v[56:57], v[36:37], v[8:9] op_sel_hi:[0,1,1]
	v_add_f32_e32 v5, v5, v38
	v_add_f32_e32 v5, v5, v39
	v_pk_fma_f32 v[10:11], v[14:15], v[20:21], v[10:11] op_sel_hi:[0,1,1]
	v_mov_b32_e32 v20, v15
	v_pk_fma_f32 v[8:9], v[14:15], v[34:35], v[8:9] op_sel_hi:[0,1,1]
	v_pk_mul_f32 v[12:13], v[14:15], v[46:47]
	v_pk_fma_f32 v[10:11], v[20:21], v[40:41], v[10:11] op_sel_hi:[0,1,1]
	v_pk_fma_f32 v[8:9], v[20:21], v[44:45], v[8:9] op_sel_hi:[0,1,1]
	v_add_f32_e32 v5, v5, v12
	v_add_f32_e32 v5, v5, v13
	v_pk_fma_f32 v[10:11], v[24:25], v[26:27], v[10:11] op_sel_hi:[0,1,1]
	v_mov_b32_e32 v14, v25
	v_pk_fma_f32 v[8:9], v[24:25], v[42:43], v[8:9] op_sel_hi:[0,1,1]
	s_waitcnt lgkmcnt(1)
	v_pk_mul_f32 v[12:13], v[24:25], v[60:61]
	v_pk_fma_f32 v[10:11], v[14:15], v[48:49], v[10:11] op_sel_hi:[0,1,1]
	v_pk_fma_f32 v[8:9], v[14:15], v[52:53], v[8:9] op_sel_hi:[0,1,1]
	v_add_f32_e32 v5, v5, v12
	v_pk_fma_f32 v[10:11], v[16:17], v[28:29], v[10:11] op_sel_hi:[0,1,1]
	v_pk_fma_f32 v[8:9], v[16:17], v[50:51], v[8:9] op_sel_hi:[0,1,1]
	v_mov_b32_e32 v17, v22
	v_add_f32_e32 v5, v5, v13
	s_waitcnt lgkmcnt(0)
	v_pk_mul_f32 v[12:13], v[16:17], v[62:63]
	v_pk_fma_f32 v[10:11], v[22:23], v[54:55], v[10:11] op_sel_hi:[0,1,1]
	v_add_f32_e32 v5, v5, v12
	v_pk_fma_f32 v[8:9], v[22:23], v[58:59], v[8:9] op_sel_hi:[0,1,1]
	v_add_f32_e32 v5, v5, v13
	ds_read2_b32 v[20:21], v18 offset1:16
	v_add_u32_e32 v54, 0x1000, v18
	v_add_u32_e32 v62, 0x4000, v18
	s_waitcnt lgkmcnt(0)
	v_mov_b32_e32 v64, v20
	ds_read2_b32 v[26:27], v18 offset0:32 offset1:48
	ds_read2_b32 v[28:29], v18 offset0:64 offset1:80
	ds_read2_b32 v[30:31], v18 offset0:96 offset1:112
	v_add_u32_e32 v17, 0x2000, v18
	v_add_u32_e32 v23, 0x3000, v18
	ds_read2_b32 v[32:33], v54 offset1:16
	ds_read2_b32 v[34:35], v17 offset1:16
	ds_read2_b32 v[36:37], v23 offset1:16
	ds_read2_b32 v[38:39], v62 offset1:16
	ds_read2_b32 v[40:41], v54 offset0:32 offset1:48
	ds_read2_b32 v[42:43], v17 offset0:32 offset1:48
	ds_read2_b32 v[44:45], v23 offset0:32 offset1:48
	ds_read2_b32 v[46:47], v62 offset0:32 offset1:48
	ds_read2_b32 v[48:49], v54 offset0:64 offset1:80
	ds_read2_b32 v[50:51], v17 offset0:64 offset1:80
	ds_read2_b32 v[52:53], v23 offset0:64 offset1:80
	ds_read2_b32 v[54:55], v54 offset0:96 offset1:112
	ds_read2_b32 v[56:57], v17 offset0:96 offset1:112
	ds_read2_b32 v[58:59], v23 offset0:96 offset1:112
	ds_read2_b32 v[60:61], v62 offset0:64 offset1:80
	ds_read2_b32 v[62:63], v62 offset0:96 offset1:112
	s_waitcnt lgkmcnt(14)
	v_mov_b32_e32 v20, v26
	v_mov_b32_e32 v26, v28
	v_mov_b32_e32 v28, v30
	v_mov_b32_e32 v65, v32
	v_mov_b32_e32 v32, v21
	s_waitcnt lgkmcnt(11)
	v_mov_b32_e32 v21, v40
	v_mov_b32_e32 v40, v27
	s_waitcnt lgkmcnt(7)
	v_mov_b32_e32 v27, v48
	v_mov_b32_e32 v48, v29
	s_waitcnt lgkmcnt(4)
	v_mov_b32_e32 v29, v54
	v_mov_b32_e32 v54, v31
	v_mov_b32_e32 v30, v34
	v_mov_b32_e32 v31, v36
	v_mov_b32_e32 v36, v35
	v_mov_b32_e32 v34, v42
	v_mov_b32_e32 v42, v50
	s_waitcnt lgkmcnt(3)
	v_mov_b32_e32 v50, v56
	v_mov_b32_e32 v35, v44
	v_mov_b32_e32 v44, v43
	v_mov_b32_e32 v43, v52
	v_mov_b32_e32 v52, v51
	s_waitcnt lgkmcnt(2)
	v_mov_b32_e32 v51, v58
	v_mov_b32_e32 v58, v57
	v_add_u32_e32 v18, 0x200, v18
	s_waitcnt vmcnt(32)
	v_mov_b32_e32 v12, v204
	v_mov_b32_e32 v13, v205
	v_mov_b32_e32 v14, v206
	v_mov_b32_e32 v15, v207
	v_mov_b32_e32 v24, v208
	v_mov_b32_e32 v25, v209
	v_mov_b32_e32 v16, v210
	v_mov_b32_e32 v22, v211
	v_pk_fma_f32 v[10:11], v[12:13], v[64:65], v[10:11] op_sel_hi:[0,1,1]
	v_mov_b32_e32 v56, v13
	v_pk_fma_f32 v[8:9], v[12:13], v[30:31], v[8:9] op_sel_hi:[0,1,1]
	v_pk_mul_f32 v[38:39], v[12:13], v[38:39]
	v_pk_fma_f32 v[10:11], v[56:57], v[32:33], v[10:11] op_sel_hi:[0,1,1]
	v_pk_fma_f32 v[8:9], v[56:57], v[36:37], v[8:9] op_sel_hi:[0,1,1]
	v_add_f32_e32 v5, v5, v38
	v_add_f32_e32 v5, v5, v39
	v_pk_fma_f32 v[10:11], v[14:15], v[20:21], v[10:11] op_sel_hi:[0,1,1]
	v_mov_b32_e32 v20, v15
	v_pk_fma_f32 v[8:9], v[14:15], v[34:35], v[8:9] op_sel_hi:[0,1,1]
	v_pk_mul_f32 v[12:13], v[14:15], v[46:47]
	v_pk_fma_f32 v[10:11], v[20:21], v[40:41], v[10:11] op_sel_hi:[0,1,1]
	v_pk_fma_f32 v[8:9], v[20:21], v[44:45], v[8:9] op_sel_hi:[0,1,1]
	v_add_f32_e32 v5, v5, v12
	v_add_f32_e32 v5, v5, v13
	v_pk_fma_f32 v[10:11], v[24:25], v[26:27], v[10:11] op_sel_hi:[0,1,1]
	v_mov_b32_e32 v14, v25
	v_pk_fma_f32 v[8:9], v[24:25], v[42:43], v[8:9] op_sel_hi:[0,1,1]
	s_waitcnt lgkmcnt(1)
	v_pk_mul_f32 v[12:13], v[24:25], v[60:61]
	v_pk_fma_f32 v[10:11], v[14:15], v[48:49], v[10:11] op_sel_hi:[0,1,1]
	v_pk_fma_f32 v[8:9], v[14:15], v[52:53], v[8:9] op_sel_hi:[0,1,1]
	v_add_f32_e32 v5, v5, v12
	v_pk_fma_f32 v[10:11], v[16:17], v[28:29], v[10:11] op_sel_hi:[0,1,1]
	v_pk_fma_f32 v[8:9], v[16:17], v[50:51], v[8:9] op_sel_hi:[0,1,1]
	v_mov_b32_e32 v17, v22
	v_add_f32_e32 v5, v5, v13
	s_waitcnt lgkmcnt(0)
	v_pk_mul_f32 v[12:13], v[16:17], v[62:63]
	v_pk_fma_f32 v[10:11], v[22:23], v[54:55], v[10:11] op_sel_hi:[0,1,1]
	v_add_f32_e32 v5, v5, v12
	v_pk_fma_f32 v[8:9], v[22:23], v[58:59], v[8:9] op_sel_hi:[0,1,1]
	v_add_f32_e32 v5, v5, v13
	ds_read2_b32 v[20:21], v18 offset1:16
	v_add_u32_e32 v54, 0x1000, v18
	v_add_u32_e32 v62, 0x4000, v18
	s_waitcnt lgkmcnt(0)
	v_mov_b32_e32 v64, v20
	ds_read2_b32 v[26:27], v18 offset0:32 offset1:48
	ds_read2_b32 v[28:29], v18 offset0:64 offset1:80
	ds_read2_b32 v[30:31], v18 offset0:96 offset1:112
	v_add_u32_e32 v17, 0x2000, v18
	v_add_u32_e32 v23, 0x3000, v18
	ds_read2_b32 v[32:33], v54 offset1:16
	ds_read2_b32 v[34:35], v17 offset1:16
	ds_read2_b32 v[36:37], v23 offset1:16
	ds_read2_b32 v[38:39], v62 offset1:16
	ds_read2_b32 v[40:41], v54 offset0:32 offset1:48
	ds_read2_b32 v[42:43], v17 offset0:32 offset1:48
	ds_read2_b32 v[44:45], v23 offset0:32 offset1:48
	ds_read2_b32 v[46:47], v62 offset0:32 offset1:48
	ds_read2_b32 v[48:49], v54 offset0:64 offset1:80
	ds_read2_b32 v[50:51], v17 offset0:64 offset1:80
	ds_read2_b32 v[52:53], v23 offset0:64 offset1:80
	ds_read2_b32 v[54:55], v54 offset0:96 offset1:112
	ds_read2_b32 v[56:57], v17 offset0:96 offset1:112
	ds_read2_b32 v[58:59], v23 offset0:96 offset1:112
	ds_read2_b32 v[60:61], v62 offset0:64 offset1:80
	ds_read2_b32 v[62:63], v62 offset0:96 offset1:112
	s_waitcnt lgkmcnt(14)
	v_mov_b32_e32 v20, v26
	v_mov_b32_e32 v26, v28
	v_mov_b32_e32 v28, v30
	v_mov_b32_e32 v65, v32
	v_mov_b32_e32 v32, v21
	s_waitcnt lgkmcnt(11)
	v_mov_b32_e32 v21, v40
	v_mov_b32_e32 v40, v27
	s_waitcnt lgkmcnt(7)
	v_mov_b32_e32 v27, v48
	v_mov_b32_e32 v48, v29
	s_waitcnt lgkmcnt(4)
	v_mov_b32_e32 v29, v54
	v_mov_b32_e32 v54, v31
	v_mov_b32_e32 v30, v34
	v_mov_b32_e32 v31, v36
	v_mov_b32_e32 v36, v35
	v_mov_b32_e32 v34, v42
	v_mov_b32_e32 v42, v50
	s_waitcnt lgkmcnt(3)
	v_mov_b32_e32 v50, v56
	v_mov_b32_e32 v35, v44
	v_mov_b32_e32 v44, v43
	v_mov_b32_e32 v43, v52
	v_mov_b32_e32 v52, v51
	s_waitcnt lgkmcnt(2)
	v_mov_b32_e32 v51, v58
	v_mov_b32_e32 v58, v57
	v_add_u32_e32 v18, 0x200, v18
	s_waitcnt vmcnt(24)
	v_mov_b32_e32 v12, v212
	v_mov_b32_e32 v13, v213
	v_mov_b32_e32 v14, v214
	v_mov_b32_e32 v15, v215
	v_mov_b32_e32 v24, v216
	v_mov_b32_e32 v25, v217
	v_mov_b32_e32 v16, v218
	v_mov_b32_e32 v22, v219
	v_pk_fma_f32 v[10:11], v[12:13], v[64:65], v[10:11] op_sel_hi:[0,1,1]
	v_mov_b32_e32 v56, v13
	v_pk_fma_f32 v[8:9], v[12:13], v[30:31], v[8:9] op_sel_hi:[0,1,1]
	v_pk_mul_f32 v[38:39], v[12:13], v[38:39]
	v_pk_fma_f32 v[10:11], v[56:57], v[32:33], v[10:11] op_sel_hi:[0,1,1]
	v_pk_fma_f32 v[8:9], v[56:57], v[36:37], v[8:9] op_sel_hi:[0,1,1]
	v_add_f32_e32 v5, v5, v38
	v_add_f32_e32 v5, v5, v39
	v_pk_fma_f32 v[10:11], v[14:15], v[20:21], v[10:11] op_sel_hi:[0,1,1]
	v_mov_b32_e32 v20, v15
	v_pk_fma_f32 v[8:9], v[14:15], v[34:35], v[8:9] op_sel_hi:[0,1,1]
	v_pk_mul_f32 v[12:13], v[14:15], v[46:47]
	v_pk_fma_f32 v[10:11], v[20:21], v[40:41], v[10:11] op_sel_hi:[0,1,1]
	v_pk_fma_f32 v[8:9], v[20:21], v[44:45], v[8:9] op_sel_hi:[0,1,1]
	v_add_f32_e32 v5, v5, v12
	v_add_f32_e32 v5, v5, v13
	v_pk_fma_f32 v[10:11], v[24:25], v[26:27], v[10:11] op_sel_hi:[0,1,1]
	v_mov_b32_e32 v14, v25
	v_pk_fma_f32 v[8:9], v[24:25], v[42:43], v[8:9] op_sel_hi:[0,1,1]
	s_waitcnt lgkmcnt(1)
	v_pk_mul_f32 v[12:13], v[24:25], v[60:61]
	v_pk_fma_f32 v[10:11], v[14:15], v[48:49], v[10:11] op_sel_hi:[0,1,1]
	v_pk_fma_f32 v[8:9], v[14:15], v[52:53], v[8:9] op_sel_hi:[0,1,1]
	v_add_f32_e32 v5, v5, v12
	v_pk_fma_f32 v[10:11], v[16:17], v[28:29], v[10:11] op_sel_hi:[0,1,1]
	v_pk_fma_f32 v[8:9], v[16:17], v[50:51], v[8:9] op_sel_hi:[0,1,1]
	v_mov_b32_e32 v17, v22
	v_add_f32_e32 v5, v5, v13
	s_waitcnt lgkmcnt(0)
	v_pk_mul_f32 v[12:13], v[16:17], v[62:63]
	v_pk_fma_f32 v[10:11], v[22:23], v[54:55], v[10:11] op_sel_hi:[0,1,1]
	v_add_f32_e32 v5, v5, v12
	v_pk_fma_f32 v[8:9], v[22:23], v[58:59], v[8:9] op_sel_hi:[0,1,1]
	v_add_f32_e32 v5, v5, v13
	ds_read2_b32 v[20:21], v18 offset1:16
	v_add_u32_e32 v54, 0x1000, v18
	v_add_u32_e32 v62, 0x4000, v18
	s_waitcnt lgkmcnt(0)
	v_mov_b32_e32 v64, v20
	ds_read2_b32 v[26:27], v18 offset0:32 offset1:48
	ds_read2_b32 v[28:29], v18 offset0:64 offset1:80
	ds_read2_b32 v[30:31], v18 offset0:96 offset1:112
	v_add_u32_e32 v17, 0x2000, v18
	v_add_u32_e32 v23, 0x3000, v18
	ds_read2_b32 v[32:33], v54 offset1:16
	ds_read2_b32 v[34:35], v17 offset1:16
	ds_read2_b32 v[36:37], v23 offset1:16
	ds_read2_b32 v[38:39], v62 offset1:16
	ds_read2_b32 v[40:41], v54 offset0:32 offset1:48
	ds_read2_b32 v[42:43], v17 offset0:32 offset1:48
	ds_read2_b32 v[44:45], v23 offset0:32 offset1:48
	ds_read2_b32 v[46:47], v62 offset0:32 offset1:48
	ds_read2_b32 v[48:49], v54 offset0:64 offset1:80
	ds_read2_b32 v[50:51], v17 offset0:64 offset1:80
	ds_read2_b32 v[52:53], v23 offset0:64 offset1:80
	ds_read2_b32 v[54:55], v54 offset0:96 offset1:112
	ds_read2_b32 v[56:57], v17 offset0:96 offset1:112
	ds_read2_b32 v[58:59], v23 offset0:96 offset1:112
	ds_read2_b32 v[60:61], v62 offset0:64 offset1:80
	ds_read2_b32 v[62:63], v62 offset0:96 offset1:112
	s_waitcnt lgkmcnt(14)
	v_mov_b32_e32 v20, v26
	v_mov_b32_e32 v26, v28
	v_mov_b32_e32 v28, v30
	v_mov_b32_e32 v65, v32
	v_mov_b32_e32 v32, v21
	s_waitcnt lgkmcnt(11)
	v_mov_b32_e32 v21, v40
	v_mov_b32_e32 v40, v27
	s_waitcnt lgkmcnt(7)
	v_mov_b32_e32 v27, v48
	v_mov_b32_e32 v48, v29
	s_waitcnt lgkmcnt(4)
	v_mov_b32_e32 v29, v54
	v_mov_b32_e32 v54, v31
	v_mov_b32_e32 v30, v34
	v_mov_b32_e32 v31, v36
	v_mov_b32_e32 v36, v35
	v_mov_b32_e32 v34, v42
	v_mov_b32_e32 v42, v50
	s_waitcnt lgkmcnt(3)
	v_mov_b32_e32 v50, v56
	v_mov_b32_e32 v35, v44
	v_mov_b32_e32 v44, v43
	v_mov_b32_e32 v43, v52
	v_mov_b32_e32 v52, v51
	s_waitcnt lgkmcnt(2)
	v_mov_b32_e32 v51, v58
	v_mov_b32_e32 v58, v57
	v_add_u32_e32 v18, 0x200, v18
	s_waitcnt vmcnt(16)
	v_mov_b32_e32 v12, v220
	v_mov_b32_e32 v13, v221
	v_mov_b32_e32 v14, v222
	v_mov_b32_e32 v15, v223
	v_mov_b32_e32 v24, v224
	v_mov_b32_e32 v25, v225
	v_mov_b32_e32 v16, v226
	v_mov_b32_e32 v22, v227
	v_pk_fma_f32 v[10:11], v[12:13], v[64:65], v[10:11] op_sel_hi:[0,1,1]
	v_mov_b32_e32 v56, v13
	v_pk_fma_f32 v[8:9], v[12:13], v[30:31], v[8:9] op_sel_hi:[0,1,1]
	v_pk_mul_f32 v[38:39], v[12:13], v[38:39]
	v_pk_fma_f32 v[10:11], v[56:57], v[32:33], v[10:11] op_sel_hi:[0,1,1]
	v_pk_fma_f32 v[8:9], v[56:57], v[36:37], v[8:9] op_sel_hi:[0,1,1]
	v_add_f32_e32 v5, v5, v38
	v_add_f32_e32 v5, v5, v39
	v_pk_fma_f32 v[10:11], v[14:15], v[20:21], v[10:11] op_sel_hi:[0,1,1]
	v_mov_b32_e32 v20, v15
	v_pk_fma_f32 v[8:9], v[14:15], v[34:35], v[8:9] op_sel_hi:[0,1,1]
	v_pk_mul_f32 v[12:13], v[14:15], v[46:47]
	v_pk_fma_f32 v[10:11], v[20:21], v[40:41], v[10:11] op_sel_hi:[0,1,1]
	v_pk_fma_f32 v[8:9], v[20:21], v[44:45], v[8:9] op_sel_hi:[0,1,1]
	v_add_f32_e32 v5, v5, v12
	v_add_f32_e32 v5, v5, v13
	v_pk_fma_f32 v[10:11], v[24:25], v[26:27], v[10:11] op_sel_hi:[0,1,1]
	v_mov_b32_e32 v14, v25
	v_pk_fma_f32 v[8:9], v[24:25], v[42:43], v[8:9] op_sel_hi:[0,1,1]
	s_waitcnt lgkmcnt(1)
	v_pk_mul_f32 v[12:13], v[24:25], v[60:61]
	v_pk_fma_f32 v[10:11], v[14:15], v[48:49], v[10:11] op_sel_hi:[0,1,1]
	v_pk_fma_f32 v[8:9], v[14:15], v[52:53], v[8:9] op_sel_hi:[0,1,1]
	v_add_f32_e32 v5, v5, v12
	v_pk_fma_f32 v[10:11], v[16:17], v[28:29], v[10:11] op_sel_hi:[0,1,1]
	v_pk_fma_f32 v[8:9], v[16:17], v[50:51], v[8:9] op_sel_hi:[0,1,1]
	v_mov_b32_e32 v17, v22
	v_add_f32_e32 v5, v5, v13
	s_waitcnt lgkmcnt(0)
	v_pk_mul_f32 v[12:13], v[16:17], v[62:63]
	v_pk_fma_f32 v[10:11], v[22:23], v[54:55], v[10:11] op_sel_hi:[0,1,1]
	v_add_f32_e32 v5, v5, v12
	v_pk_fma_f32 v[8:9], v[22:23], v[58:59], v[8:9] op_sel_hi:[0,1,1]
	v_add_f32_e32 v5, v5, v13
	ds_read2_b32 v[20:21], v18 offset1:16
	v_add_u32_e32 v54, 0x1000, v18
	v_add_u32_e32 v62, 0x4000, v18
	s_waitcnt lgkmcnt(0)
	v_mov_b32_e32 v64, v20
	ds_read2_b32 v[26:27], v18 offset0:32 offset1:48
	ds_read2_b32 v[28:29], v18 offset0:64 offset1:80
	ds_read2_b32 v[30:31], v18 offset0:96 offset1:112
	v_add_u32_e32 v17, 0x2000, v18
	v_add_u32_e32 v23, 0x3000, v18
	ds_read2_b32 v[32:33], v54 offset1:16
	ds_read2_b32 v[34:35], v17 offset1:16
	ds_read2_b32 v[36:37], v23 offset1:16
	ds_read2_b32 v[38:39], v62 offset1:16
	ds_read2_b32 v[40:41], v54 offset0:32 offset1:48
	ds_read2_b32 v[42:43], v17 offset0:32 offset1:48
	ds_read2_b32 v[44:45], v23 offset0:32 offset1:48
	ds_read2_b32 v[46:47], v62 offset0:32 offset1:48
	ds_read2_b32 v[48:49], v54 offset0:64 offset1:80
	ds_read2_b32 v[50:51], v17 offset0:64 offset1:80
	ds_read2_b32 v[52:53], v23 offset0:64 offset1:80
	ds_read2_b32 v[54:55], v54 offset0:96 offset1:112
	ds_read2_b32 v[56:57], v17 offset0:96 offset1:112
	ds_read2_b32 v[58:59], v23 offset0:96 offset1:112
	ds_read2_b32 v[60:61], v62 offset0:64 offset1:80
	ds_read2_b32 v[62:63], v62 offset0:96 offset1:112
	s_waitcnt lgkmcnt(14)
	v_mov_b32_e32 v20, v26
	v_mov_b32_e32 v26, v28
	v_mov_b32_e32 v28, v30
	v_mov_b32_e32 v65, v32
	v_mov_b32_e32 v32, v21
	s_waitcnt lgkmcnt(11)
	v_mov_b32_e32 v21, v40
	v_mov_b32_e32 v40, v27
	s_waitcnt lgkmcnt(7)
	v_mov_b32_e32 v27, v48
	v_mov_b32_e32 v48, v29
	s_waitcnt lgkmcnt(4)
	v_mov_b32_e32 v29, v54
	v_mov_b32_e32 v54, v31
	v_mov_b32_e32 v30, v34
	v_mov_b32_e32 v31, v36
	v_mov_b32_e32 v36, v35
	v_mov_b32_e32 v34, v42
	v_mov_b32_e32 v42, v50
	s_waitcnt lgkmcnt(3)
	v_mov_b32_e32 v50, v56
	v_mov_b32_e32 v35, v44
	v_mov_b32_e32 v44, v43
	v_mov_b32_e32 v43, v52
	v_mov_b32_e32 v52, v51
	s_waitcnt lgkmcnt(2)
	v_mov_b32_e32 v51, v58
	v_mov_b32_e32 v58, v57
	v_add_u32_e32 v18, 0x200, v18
	s_waitcnt vmcnt(8)
	v_mov_b32_e32 v12, v228
	v_mov_b32_e32 v13, v229
	v_mov_b32_e32 v14, v230
	v_mov_b32_e32 v15, v231
	v_mov_b32_e32 v24, v232
	v_mov_b32_e32 v25, v233
	v_mov_b32_e32 v16, v234
	v_mov_b32_e32 v22, v235
	v_pk_fma_f32 v[10:11], v[12:13], v[64:65], v[10:11] op_sel_hi:[0,1,1]
	v_mov_b32_e32 v56, v13
	v_pk_fma_f32 v[8:9], v[12:13], v[30:31], v[8:9] op_sel_hi:[0,1,1]
	v_pk_mul_f32 v[38:39], v[12:13], v[38:39]
	v_pk_fma_f32 v[10:11], v[56:57], v[32:33], v[10:11] op_sel_hi:[0,1,1]
	v_pk_fma_f32 v[8:9], v[56:57], v[36:37], v[8:9] op_sel_hi:[0,1,1]
	v_add_f32_e32 v5, v5, v38
	v_add_f32_e32 v5, v5, v39
	v_pk_fma_f32 v[10:11], v[14:15], v[20:21], v[10:11] op_sel_hi:[0,1,1]
	v_mov_b32_e32 v20, v15
	v_pk_fma_f32 v[8:9], v[14:15], v[34:35], v[8:9] op_sel_hi:[0,1,1]
	v_pk_mul_f32 v[12:13], v[14:15], v[46:47]
	v_pk_fma_f32 v[10:11], v[20:21], v[40:41], v[10:11] op_sel_hi:[0,1,1]
	v_pk_fma_f32 v[8:9], v[20:21], v[44:45], v[8:9] op_sel_hi:[0,1,1]
	v_add_f32_e32 v5, v5, v12
	v_add_f32_e32 v5, v5, v13
	v_pk_fma_f32 v[10:11], v[24:25], v[26:27], v[10:11] op_sel_hi:[0,1,1]
	v_mov_b32_e32 v14, v25
	v_pk_fma_f32 v[8:9], v[24:25], v[42:43], v[8:9] op_sel_hi:[0,1,1]
	s_waitcnt lgkmcnt(1)
	v_pk_mul_f32 v[12:13], v[24:25], v[60:61]
	v_pk_fma_f32 v[10:11], v[14:15], v[48:49], v[10:11] op_sel_hi:[0,1,1]
	v_pk_fma_f32 v[8:9], v[14:15], v[52:53], v[8:9] op_sel_hi:[0,1,1]
	v_add_f32_e32 v5, v5, v12
	v_pk_fma_f32 v[10:11], v[16:17], v[28:29], v[10:11] op_sel_hi:[0,1,1]
	v_pk_fma_f32 v[8:9], v[16:17], v[50:51], v[8:9] op_sel_hi:[0,1,1]
	v_mov_b32_e32 v17, v22
	v_add_f32_e32 v5, v5, v13
	s_waitcnt lgkmcnt(0)
	v_pk_mul_f32 v[12:13], v[16:17], v[62:63]
	v_pk_fma_f32 v[10:11], v[22:23], v[54:55], v[10:11] op_sel_hi:[0,1,1]
	v_add_f32_e32 v5, v5, v12
	v_pk_fma_f32 v[8:9], v[22:23], v[58:59], v[8:9] op_sel_hi:[0,1,1]
	v_add_f32_e32 v5, v5, v13
	ds_read2_b32 v[20:21], v18 offset1:16
	v_add_u32_e32 v54, 0x1000, v18
	v_add_u32_e32 v62, 0x4000, v18
	s_waitcnt lgkmcnt(0)
	v_mov_b32_e32 v64, v20
	ds_read2_b32 v[26:27], v18 offset0:32 offset1:48
	ds_read2_b32 v[28:29], v18 offset0:64 offset1:80
	ds_read2_b32 v[30:31], v18 offset0:96 offset1:112
	v_add_u32_e32 v17, 0x2000, v18
	v_add_u32_e32 v23, 0x3000, v18
	ds_read2_b32 v[32:33], v54 offset1:16
	ds_read2_b32 v[34:35], v17 offset1:16
	ds_read2_b32 v[36:37], v23 offset1:16
	ds_read2_b32 v[38:39], v62 offset1:16
	ds_read2_b32 v[40:41], v54 offset0:32 offset1:48
	ds_read2_b32 v[42:43], v17 offset0:32 offset1:48
	ds_read2_b32 v[44:45], v23 offset0:32 offset1:48
	ds_read2_b32 v[46:47], v62 offset0:32 offset1:48
	ds_read2_b32 v[48:49], v54 offset0:64 offset1:80
	ds_read2_b32 v[50:51], v17 offset0:64 offset1:80
	ds_read2_b32 v[52:53], v23 offset0:64 offset1:80
	ds_read2_b32 v[54:55], v54 offset0:96 offset1:112
	ds_read2_b32 v[56:57], v17 offset0:96 offset1:112
	ds_read2_b32 v[58:59], v23 offset0:96 offset1:112
	ds_read2_b32 v[60:61], v62 offset0:64 offset1:80
	ds_read2_b32 v[62:63], v62 offset0:96 offset1:112
	s_waitcnt lgkmcnt(14)
	v_mov_b32_e32 v20, v26
	v_mov_b32_e32 v26, v28
	v_mov_b32_e32 v28, v30
	v_mov_b32_e32 v65, v32
	v_mov_b32_e32 v32, v21
	s_waitcnt lgkmcnt(11)
	v_mov_b32_e32 v21, v40
	v_mov_b32_e32 v40, v27
	s_waitcnt lgkmcnt(7)
	v_mov_b32_e32 v27, v48
	v_mov_b32_e32 v48, v29
	s_waitcnt lgkmcnt(4)
	v_mov_b32_e32 v29, v54
	v_mov_b32_e32 v54, v31
	v_mov_b32_e32 v30, v34
	v_mov_b32_e32 v31, v36
	v_mov_b32_e32 v36, v35
	v_mov_b32_e32 v34, v42
	v_mov_b32_e32 v42, v50
	s_waitcnt lgkmcnt(3)
	v_mov_b32_e32 v50, v56
	v_mov_b32_e32 v35, v44
	v_mov_b32_e32 v44, v43
	v_mov_b32_e32 v43, v52
	v_mov_b32_e32 v52, v51
	s_waitcnt lgkmcnt(2)
	v_mov_b32_e32 v51, v58
	v_mov_b32_e32 v58, v57
	v_add_u32_e32 v18, 0x200, v18
	s_waitcnt vmcnt(0)
	v_mov_b32_e32 v12, v236
	v_mov_b32_e32 v13, v237
	v_mov_b32_e32 v14, v238
	v_mov_b32_e32 v15, v239
	v_mov_b32_e32 v24, v240
	v_mov_b32_e32 v25, v241
	v_mov_b32_e32 v16, v242
	v_mov_b32_e32 v22, v243
	v_pk_fma_f32 v[10:11], v[12:13], v[64:65], v[10:11] op_sel_hi:[0,1,1]
	v_mov_b32_e32 v56, v13
	v_pk_fma_f32 v[8:9], v[12:13], v[30:31], v[8:9] op_sel_hi:[0,1,1]
	v_pk_mul_f32 v[38:39], v[12:13], v[38:39]
	v_pk_fma_f32 v[10:11], v[56:57], v[32:33], v[10:11] op_sel_hi:[0,1,1]
	v_pk_fma_f32 v[8:9], v[56:57], v[36:37], v[8:9] op_sel_hi:[0,1,1]
	v_add_f32_e32 v5, v5, v38
	v_add_f32_e32 v5, v5, v39
	v_pk_fma_f32 v[10:11], v[14:15], v[20:21], v[10:11] op_sel_hi:[0,1,1]
	v_mov_b32_e32 v20, v15
	v_pk_fma_f32 v[8:9], v[14:15], v[34:35], v[8:9] op_sel_hi:[0,1,1]
	v_pk_mul_f32 v[12:13], v[14:15], v[46:47]
	v_pk_fma_f32 v[10:11], v[20:21], v[40:41], v[10:11] op_sel_hi:[0,1,1]
	v_pk_fma_f32 v[8:9], v[20:21], v[44:45], v[8:9] op_sel_hi:[0,1,1]
	v_add_f32_e32 v5, v5, v12
	v_add_f32_e32 v5, v5, v13
	v_pk_fma_f32 v[10:11], v[24:25], v[26:27], v[10:11] op_sel_hi:[0,1,1]
	v_mov_b32_e32 v14, v25
	v_pk_fma_f32 v[8:9], v[24:25], v[42:43], v[8:9] op_sel_hi:[0,1,1]
	s_waitcnt lgkmcnt(1)
	v_pk_mul_f32 v[12:13], v[24:25], v[60:61]
	v_pk_fma_f32 v[10:11], v[14:15], v[48:49], v[10:11] op_sel_hi:[0,1,1]
	v_pk_fma_f32 v[8:9], v[14:15], v[52:53], v[8:9] op_sel_hi:[0,1,1]
	v_add_f32_e32 v5, v5, v12
	v_pk_fma_f32 v[10:11], v[16:17], v[28:29], v[10:11] op_sel_hi:[0,1,1]
	v_pk_fma_f32 v[8:9], v[16:17], v[50:51], v[8:9] op_sel_hi:[0,1,1]
	v_mov_b32_e32 v17, v22
	v_add_f32_e32 v5, v5, v13
	s_waitcnt lgkmcnt(0)
	v_pk_mul_f32 v[12:13], v[16:17], v[62:63]
	v_pk_fma_f32 v[10:11], v[22:23], v[54:55], v[10:11] op_sel_hi:[0,1,1]
	v_add_f32_e32 v5, v5, v12
	v_pk_fma_f32 v[8:9], v[22:23], v[58:59], v[8:9] op_sel_hi:[0,1,1]
	v_add_f32_e32 v5, v5, v13
	s_or_b64 exec, exec, s[4:5]

.LBB0_59:
	v_mov_b32_e32 v210, 0
	v_mov_b32_e32 v211, 0
	v_mov_b32_e32 v212, 0
	v_mov_b32_e32 v213, 0
	v_mov_b32_e32 v214, 0
	v_mov_b32_e32 v215, 0
	v_mov_b32_e32 v216, 0
	v_mov_b32_e32 v217, 0
	v_mov_b32_e32 v218, 0
	v_mov_b32_e32 v219, 0
	v_mov_b32_e32 v220, 0
	v_mov_b32_e32 v221, 0
	v_mov_b32_e32 v222, 0
	v_mov_b32_e32 v223, 0
	v_mov_b32_e32 v224, 0
	v_mov_b32_e32 v225, 0
	v_mov_b32_e32 v226, 0
	v_mov_b32_e32 v227, 0
	v_mov_b32_e32 v228, 0
	v_mov_b32_e32 v229, 0
	v_mov_b32_e32 v230, 0
	v_mov_b32_e32 v231, 0
	v_mov_b32_e32 v232, 0
	v_mov_b32_e32 v233, 0
	v_mov_b32_e32 v234, 0
	v_mov_b32_e32 v235, 0
	v_mov_b32_e32 v236, 0
	v_mov_b32_e32 v237, 0
	v_mov_b32_e32 v238, 0
	v_mov_b32_e32 v239, 0
	v_mov_b32_e32 v240, 0
	v_mov_b32_e32 v241, 0
	s_and_saveexec_b64 s[8:9], vcc
	v_lshl_add_u64 v[244:245], v[22:23], 0, s[4:5]
	global_load_dword v210, v[244:245], off nt
	v_lshl_add_u64 v[244:245], v[20:21], 0, s[4:5]
	global_load_dword v211, v[244:245], off nt
	v_lshl_add_u64 v[244:245], v[18:19], 0, s[4:5]
	global_load_dword v212, v[244:245], off nt
	v_lshl_add_u64 v[244:245], v[16:17], 0, s[4:5]
	global_load_dword v213, v[244:245], off nt
	v_lshl_add_u64 v[244:245], v[14:15], 0, s[4:5]
	global_load_dword v214, v[244:245], off nt
	v_lshl_add_u64 v[244:245], v[12:13], 0, s[4:5]
	global_load_dword v215, v[244:245], off nt
	v_lshl_add_u64 v[244:245], v[10:11], 0, s[4:5]
	global_load_dword v216, v[244:245], off nt
	v_lshl_add_u64 v[244:245], v[8:9], 0, s[4:5]
	global_load_dword v217, v[244:245], off nt
	s_add_u32 s4, s4, 0x4ac00
	s_addc_u32 s5, s5, 0
	v_lshl_add_u64 v[244:245], v[22:23], 0, s[4:5]
	global_load_dword v218, v[244:245], off nt
	v_lshl_add_u64 v[244:245], v[20:21], 0, s[4:5]
	global_load_dword v219, v[244:245], off nt
	v_lshl_add_u64 v[244:245], v[18:19], 0, s[4:5]
	global_load_dword v220, v[244:245], off nt
	v_lshl_add_u64 v[244:245], v[16:17], 0, s[4:5]
	global_load_dword v221, v[244:245], off nt
	v_lshl_add_u64 v[244:245], v[14:15], 0, s[4:5]
	global_load_dword v222, v[244:245], off nt
	v_lshl_add_u64 v[244:245], v[12:13], 0, s[4:5]
	global_load_dword v223, v[244:245], off nt
	v_lshl_add_u64 v[244:245], v[10:11], 0, s[4:5]
	global_load_dword v224, v[244:245], off nt
	v_lshl_add_u64 v[244:245], v[8:9], 0, s[4:5]
	global_load_dword v225, v[244:245], off nt
	s_add_u32 s4, s4, 0x4ac00
	s_addc_u32 s5, s5, 0
	v_lshl_add_u64 v[244:245], v[22:23], 0, s[4:5]
	global_load_dword v226, v[244:245], off nt
	v_lshl_add_u64 v[244:245], v[20:21], 0, s[4:5]
	global_load_dword v227, v[244:245], off nt
	v_lshl_add_u64 v[244:245], v[18:19], 0, s[4:5]
	global_load_dword v228, v[244:245], off nt
	v_lshl_add_u64 v[244:245], v[16:17], 0, s[4:5]
	global_load_dword v229, v[244:245], off nt
	v_lshl_add_u64 v[244:245], v[14:15], 0, s[4:5]
	global_load_dword v230, v[244:245], off nt
	v_lshl_add_u64 v[244:245], v[12:13], 0, s[4:5]
	global_load_dword v231, v[244:245], off nt
	v_lshl_add_u64 v[244:245], v[10:11], 0, s[4:5]
	global_load_dword v232, v[244:245], off nt
	v_lshl_add_u64 v[244:245], v[8:9], 0, s[4:5]
	global_load_dword v233, v[244:245], off nt
	s_add_u32 s4, s4, 0x4ac00
	s_addc_u32 s5, s5, 0
	v_lshl_add_u64 v[244:245], v[22:23], 0, s[4:5]
	global_load_dword v234, v[244:245], off nt
	v_lshl_add_u64 v[244:245], v[20:21], 0, s[4:5]
	global_load_dword v235, v[244:245], off nt
	v_lshl_add_u64 v[244:245], v[18:19], 0, s[4:5]
	global_load_dword v236, v[244:245], off nt
	v_lshl_add_u64 v[244:245], v[16:17], 0, s[4:5]
	global_load_dword v237, v[244:245], off nt
	v_lshl_add_u64 v[244:245], v[14:15], 0, s[4:5]
	global_load_dword v238, v[244:245], off nt
	v_lshl_add_u64 v[244:245], v[12:13], 0, s[4:5]
	global_load_dword v239, v[244:245], off nt
	v_lshl_add_u64 v[244:245], v[10:11], 0, s[4:5]
	global_load_dword v240, v[244:245], off nt
	v_lshl_add_u64 v[244:245], v[8:9], 0, s[4:5]
	global_load_dword v241, v[244:245], off nt
	s_add_u32 s4, s4, 0x4ac00
	s_addc_u32 s5, s5, 0
	s_or_b64 exec, exec, s[8:9]
	s_waitcnt vmcnt(0)
	ds_write_b32 v2, v210
	ds_write_b32 v2, v211 offset:264
	ds_write_b32 v2, v212 offset:528
	ds_write_b32 v2, v213 offset:792
	ds_write_b32 v2, v214 offset:1056
	ds_write_b32 v2, v215 offset:1320
	ds_write_b32 v2, v216 offset:1584
	ds_write_b32 v2, v217 offset:1848
	ds_write_b32 v2, v218 offset:2112
	ds_write_b32 v2, v219 offset:2376
	ds_write_b32 v2, v220 offset:2640
	ds_write_b32 v2, v221 offset:2904
	ds_write_b32 v2, v222 offset:3168
	ds_write_b32 v2, v223 offset:3432
	ds_write_b32 v2, v224 offset:3696
	ds_write_b32 v2, v225 offset:3960
	ds_write_b32 v2, v226 offset:4224
	ds_write_b32 v2, v227 offset:4488
	ds_write_b32 v2, v228 offset:4752
	ds_write_b32 v2, v229 offset:5016
	ds_write_b32 v2, v230 offset:5280
	ds_write_b32 v2, v231 offset:5544
	ds_write_b32 v2, v232 offset:5808
	ds_write_b32 v2, v233 offset:6072
	ds_write_b32 v2, v234 offset:6336
	ds_write_b32 v2, v235 offset:6600
	ds_write_b32 v2, v236 offset:6864
	ds_write_b32 v2, v237 offset:7128
	ds_write_b32 v2, v238 offset:7392
	ds_write_b32 v2, v239 offset:7656
	ds_write_b32 v2, v240 offset:7920
	ds_write_b32 v2, v241 offset:8184
	s_branch .LBB0_36

.LBB0_89:
	s_lshl_b32 s43, s40, 1
	s_lshl_b32 s42, s39, 1
	v_or_b32_e32 v6, s43, v30
	s_add_i32 s45, s43, 4
	s_add_i32 s44, s42, 4
	s_add_i32 s46, s42, 8
	s_add_i32 s47, s43, 8
	v_lshlrev_b64 v[70:71], 12, v[6:7]
	v_or_b32_e32 v6, s45, v30
	v_mov_b32_e32 v35, v7
	v_mov_b32_e32 v37, v7
	v_mov_b32_e32 v39, v7
	v_or_b32_e32 v34, s42, v3
	s_add_i32 s48, s42, 12
	s_add_i32 s49, s43, 12
	s_add_i32 s50, s42, 16
	s_add_i32 s52, s42, 20
	s_add_i32 s54, s42, 24
	s_add_i32 s56, s42, 28
	v_or_b32_e32 v36, s44, v3
	v_or_b32_e32 v38, s46, v3
	v_lshlrev_b64 v[72:73], 12, v[6:7]
	v_or_b32_e32 v6, s47, v30
	v_mov_b32_e32 v41, v7
	v_mov_b32_e32 v43, v7
	v_mov_b32_e32 v45, v7
	v_mov_b32_e32 v67, v7
	v_mov_b32_e32 v69, v7
	s_add_i32 s51, s43, 16
	v_lshlrev_b64 v[34:35], 12, v[34:35]
	v_or_b32_e32 v40, s48, v3
	v_or_b32_e32 v42, s50, v3
	v_or_b32_e32 v44, s52, v3
	v_or_b32_e32 v66, s54, v3
	v_or_b32_e32 v68, s56, v3
	v_lshl_add_u64 v[70:71], v[28:29], 0, v[70:71]
	v_lshlrev_b64 v[36:37], 12, v[36:37]
	v_lshlrev_b64 v[38:39], 12, v[38:39]
	v_lshlrev_b64 v[74:75], 12, v[6:7]
	v_or_b32_e32 v6, s49, v30
	s_add_i32 s53, s43, 20
	v_lshl_add_u64 v[34:35], v[28:29], 0, v[34:35]
	v_lshlrev_b64 v[40:41], 12, v[40:41]
	v_lshlrev_b64 v[42:43], 12, v[42:43]
	v_lshlrev_b64 v[44:45], 12, v[44:45]
	v_lshlrev_b64 v[66:67], 12, v[66:67]
	v_lshlrev_b64 v[68:69], 12, v[68:69]
	v_lshl_add_u64 v[72:73], v[28:29], 0, v[72:73]
	v_lshl_add_u64 v[36:37], v[28:29], 0, v[36:37]
	v_lshl_add_u64 v[38:39], v[28:29], 0, v[38:39]
	global_load_dword v33, v[70:71], off nt
	global_load_dword v65, v[34:35], off nt
	v_lshlrev_b64 v[70:71], 12, v[6:7]
	v_or_b32_e32 v6, s51, v30
	s_add_i32 s55, s43, 24
	v_lshl_add_u64 v[40:41], v[28:29], 0, v[40:41]
	v_lshl_add_u64 v[42:43], v[28:29], 0, v[42:43]
	v_lshl_add_u64 v[44:45], v[28:29], 0, v[44:45]
	v_lshl_add_u64 v[66:67], v[28:29], 0, v[66:67]
	v_lshl_add_u64 v[68:69], v[28:29], 0, v[68:69]
	global_load_dword v86, v[72:73], off nt
	global_load_dword v87, v[36:37], off nt
	global_load_dword v88, v[38:39], off nt
	global_load_dword v89, v[40:41], off nt
	global_load_dword v90, v[42:43], off nt
	global_load_dword v91, v[44:45], off nt
	global_load_dword v92, v[66:67], off nt
	global_load_dword v93, v[68:69], off nt
	v_lshl_add_u64 v[36:37], v[28:29], 0, v[70:71]
	v_lshlrev_b64 v[38:39], 12, v[6:7]
	v_or_b32_e32 v6, s53, v30
	s_add_i32 s57, s43, 28
	v_lshl_add_u64 v[34:35], v[28:29], 0, v[74:75]
	global_load_dword v94, v[36:37], off nt
	global_load_dword v95, v[34:35], off nt
	v_lshlrev_b64 v[36:37], 12, v[6:7]
	v_or_b32_e32 v6, s55, v30
	v_lshl_add_u64 v[34:35], v[28:29], 0, v[38:39]
	v_lshlrev_b64 v[38:39], 12, v[6:7]
	v_or_b32_e32 v6, s57, v30
	v_lshlrev_b64 v[40:41], 12, v[6:7]
	v_lshl_add_u64 v[40:41], v[28:29], 0, v[40:41]
	v_lshl_add_u64 v[36:37], v[28:29], 0, v[36:37]
	v_lshl_add_u64 v[38:39], v[28:29], 0, v[38:39]
	global_load_dword v6, v[40:41], off nt
	global_load_dword v96, v[38:39], off nt
	global_load_dword v97, v[36:37], off nt
	global_load_dword v98, v[34:35], off nt
	v_or_b32_e32 v36, s42, v1
	v_or_b32_e32 v34, s43, v2
	s_add_i32 s40, s40, 16
	s_add_i32 s39, s39, 16
	s_add_i32 s41, s41, -16
	v_mad_u64_u32 v[34:35], s[42:43], v34, s25, v[4:5]
	v_mad_u64_u32 v[36:37], s[42:43], v36, s25, v[4:5]
	v_or_b32_e32 v35, s44, v1
	v_or_b32_e32 v37, s45, v2
	v_or_b32_e32 v44, s46, v1
	v_or_b32_e32 v42, s47, v2
	v_or_b32_e32 v68, s48, v1
	v_or_b32_e32 v66, s49, v2
	v_or_b32_e32 v72, s50, v1
	v_or_b32_e32 v70, s51, v2
	v_or_b32_e32 v76, s52, v1
	v_or_b32_e32 v74, s53, v2
	v_or_b32_e32 v80, s54, v1
	v_or_b32_e32 v78, s55, v2
	v_or_b32_e32 v84, s56, v1
	v_or_b32_e32 v82, s57, v2
	s_cmp_lg_u32 s41, 0
	v_mad_u64_u32 v[38:39], s[42:43], v37, s25, v[4:5]
	v_mad_u64_u32 v[40:41], s[42:43], v35, s25, v[4:5]
	v_mad_u64_u32 v[42:43], s[42:43], v42, s25, v[4:5]
	v_mad_u64_u32 v[44:45], s[42:43], v44, s25, v[4:5]
	v_mad_u64_u32 v[66:67], s[42:43], v66, s25, v[4:5]
	v_mad_u64_u32 v[68:69], s[42:43], v68, s25, v[4:5]
	v_mad_u64_u32 v[70:71], s[42:43], v70, s25, v[4:5]
	v_mad_u64_u32 v[72:73], s[42:43], v72, s25, v[4:5]
	v_mad_u64_u32 v[74:75], s[42:43], v74, s25, v[4:5]
	v_mad_u64_u32 v[76:77], s[42:43], v76, s25, v[4:5]
	v_mad_u64_u32 v[78:79], s[42:43], v78, s25, v[4:5]
	v_mad_u64_u32 v[80:81], s[42:43], v80, s25, v[4:5]
	v_mad_u64_u32 v[82:83], s[42:43], v82, s25, v[4:5]
	v_mad_u64_u32 v[84:85], s[42:43], v84, s25, v[4:5]
	s_waitcnt vmcnt(15)
	ds_write_b32 v34, v33
	s_waitcnt vmcnt(14)
	ds_write_b32 v36, v65
	s_waitcnt vmcnt(13)
	ds_write_b32 v38, v86
	s_waitcnt vmcnt(12)
	ds_write_b32 v40, v87
	s_waitcnt vmcnt(4)
	ds_write_b32 v42, v95
	ds_write_b32 v44, v88
	ds_write_b32 v66, v94
	ds_write_b32 v68, v89
	s_waitcnt vmcnt(0)
	ds_write_b32 v70, v98
	ds_write_b32 v72, v90
	ds_write_b32 v74, v97
	ds_write_b32 v76, v91
	ds_write_b32 v78, v96
	ds_write_b32 v80, v92
	ds_write_b32 v82, v6
	ds_write_b32 v84, v93
	s_cbranch_scc1 .LBB0_89
	s_waitcnt lgkmcnt(0)
	ds_read2_b32 v[28:29], v48 offset1:33
	s_waitcnt lgkmcnt(0)
	v_cvt_pk_bf16_f32 v34, v28, v29
	ds_read2_b32 v[28:29], v48 offset0:66 offset1:99
	s_waitcnt lgkmcnt(0)
	v_cvt_pk_bf16_f32 v35, v28, v29
	ds_read2_b32 v[28:29], v48 offset0:132 offset1:165
	v_lshlrev_b32_e32 v6, 1, v32
	v_or_b32_e32 v3, v31, v47
	s_waitcnt lgkmcnt(0)
	v_cvt_pk_bf16_f32 v36, v28, v29
	ds_read2_b32 v[28:29], v48 offset0:198 offset1:231
	v_lshl_add_u64 v[38:39], v[8:9], 0, v[6:7]
	v_lshlrev_b32_e32 v6, 12, v3
	s_waitcnt lgkmcnt(0)
	v_cvt_pk_bf16_f32 v37, v28, v29
	ds_read2_b32 v[28:29], v48 offset0:8 offset1:41
	v_lshl_add_u64 v[32:33], v[38:39], 0, v[6:7]
	global_store_dwordx4 v[32:33], v[34:37], off
	s_waitcnt lgkmcnt(0)
	v_cvt_pk_bf16_f32 v32, v28, v29
	ds_read2_b32 v[28:29], v48 offset0:74 offset1:107
	s_waitcnt lgkmcnt(0)
	v_cvt_pk_bf16_f32 v33, v28, v29
	ds_read2_b32 v[28:29], v48 offset0:140 offset1:173
	v_or_b32_e32 v3, v31, v49
	s_waitcnt lgkmcnt(0)
	v_cvt_pk_bf16_f32 v34, v28, v29
	ds_read2_b32 v[28:29], v48 offset0:206 offset1:239
	v_lshlrev_b32_e32 v6, 12, v3
	s_waitcnt lgkmcnt(0)
	v_cvt_pk_bf16_f32 v35, v28, v29
	ds_read2_b32 v[28:29], v48 offset0:16 offset1:49
	v_lshl_add_u64 v[36:37], v[38:39], 0, v[6:7]
	global_store_dwordx4 v[36:37], v[32:35], off
	v_or_b32_e32 v3, v31, v50
	v_lshlrev_b32_e32 v6, 12, v3
	s_waitcnt lgkmcnt(0)
	v_cvt_pk_bf16_f32 v32, v28, v29
	ds_read2_b32 v[28:29], v48 offset0:82 offset1:115
	s_waitcnt lgkmcnt(0)
	v_cvt_pk_bf16_f32 v33, v28, v29
	ds_read2_b32 v[28:29], v48 offset0:148 offset1:181
	s_waitcnt lgkmcnt(0)
	v_cvt_pk_bf16_f32 v34, v28, v29
	ds_read2_b32 v[28:29], v48 offset0:214 offset1:247
	s_waitcnt lgkmcnt(0)
	v_cvt_pk_bf16_f32 v35, v28, v29
	ds_read2_b32 v[28:29], v48 offset0:24 offset1:57
	v_lshl_add_u64 v[36:37], v[38:39], 0, v[6:7]
	global_store_dwordx4 v[36:37], v[32:35], off
	s_waitcnt lgkmcnt(0)
	v_cvt_pk_bf16_f32 v28, v28, v29
	ds_read2_b32 v[32:33], v48 offset0:90 offset1:123
	s_waitcnt lgkmcnt(0)
	v_cvt_pk_bf16_f32 v29, v32, v33
	ds_read2_b32 v[32:33], v48 offset0:156 offset1:189
	v_or_b32_e32 v3, v31, v51
	s_waitcnt lgkmcnt(0)
	v_cvt_pk_bf16_f32 v30, v32, v33
	ds_read2_b32 v[32:33], v48 offset0:222 offset1:255
	v_lshlrev_b32_e32 v6, 12, v3
	s_waitcnt lgkmcnt(0)
	v_cvt_pk_bf16_f32 v31, v32, v33
	v_lshl_add_u64 v[32:33], v[38:39], 0, v[6:7]
	global_store_dwordx4 v[32:33], v[28:31], off
	s_waitcnt lgkmcnt(0)

.LBB0_93:
	s_lshl_b32 s43, s40, 1
	s_lshl_b32 s42, s39, 1
	v_or_b32_e32 v6, s43, v30
	s_add_i32 s45, s43, 4
	s_add_i32 s44, s42, 4
	s_add_i32 s46, s42, 8
	s_add_i32 s47, s43, 8
	v_lshlrev_b64 v[70:71], 12, v[6:7]
	v_or_b32_e32 v6, s45, v30
	v_mov_b32_e32 v35, v7
	v_mov_b32_e32 v37, v7
	v_mov_b32_e32 v39, v7
	v_or_b32_e32 v34, s42, v3
	s_add_i32 s48, s42, 12
	s_add_i32 s49, s43, 12
	s_add_i32 s50, s42, 16
	s_add_i32 s52, s42, 20
	s_add_i32 s54, s42, 24
	s_add_i32 s56, s42, 28
	v_or_b32_e32 v36, s44, v3
	v_or_b32_e32 v38, s46, v3
	v_lshlrev_b64 v[72:73], 12, v[6:7]
	v_or_b32_e32 v6, s47, v30
	v_mov_b32_e32 v41, v7
	v_mov_b32_e32 v43, v7
	v_mov_b32_e32 v45, v7
	v_mov_b32_e32 v67, v7
	v_mov_b32_e32 v69, v7
	s_add_i32 s51, s43, 16
	v_lshlrev_b64 v[34:35], 12, v[34:35]
	v_or_b32_e32 v40, s48, v3
	v_or_b32_e32 v42, s50, v3
	v_or_b32_e32 v44, s52, v3
	v_or_b32_e32 v66, s54, v3
	v_or_b32_e32 v68, s56, v3
	v_lshl_add_u64 v[70:71], v[28:29], 0, v[70:71]
	v_lshlrev_b64 v[36:37], 12, v[36:37]
	v_lshlrev_b64 v[38:39], 12, v[38:39]
	v_lshlrev_b64 v[74:75], 12, v[6:7]
	v_or_b32_e32 v6, s49, v30
	s_add_i32 s53, s43, 20
	v_lshl_add_u64 v[34:35], v[28:29], 0, v[34:35]
	v_lshlrev_b64 v[40:41], 12, v[40:41]
	v_lshlrev_b64 v[42:43], 12, v[42:43]
	v_lshlrev_b64 v[44:45], 12, v[44:45]
	v_lshlrev_b64 v[66:67], 12, v[66:67]
	v_lshlrev_b64 v[68:69], 12, v[68:69]
	v_lshl_add_u64 v[72:73], v[28:29], 0, v[72:73]
	v_lshl_add_u64 v[36:37], v[28:29], 0, v[36:37]
	v_lshl_add_u64 v[38:39], v[28:29], 0, v[38:39]
	global_load_dword v33, v[70:71], off nt
	global_load_dword v65, v[34:35], off nt
	v_lshlrev_b64 v[70:71], 12, v[6:7]
	v_or_b32_e32 v6, s51, v30
	s_add_i32 s55, s43, 24
	v_lshl_add_u64 v[40:41], v[28:29], 0, v[40:41]
	v_lshl_add_u64 v[42:43], v[28:29], 0, v[42:43]
	v_lshl_add_u64 v[44:45], v[28:29], 0, v[44:45]
	v_lshl_add_u64 v[66:67], v[28:29], 0, v[66:67]
	v_lshl_add_u64 v[68:69], v[28:29], 0, v[68:69]
	global_load_dword v86, v[72:73], off nt
	global_load_dword v87, v[36:37], off nt
	global_load_dword v88, v[38:39], off nt
	global_load_dword v89, v[40:41], off nt
	global_load_dword v90, v[42:43], off nt
	global_load_dword v91, v[44:45], off nt
	global_load_dword v92, v[66:67], off nt
	global_load_dword v93, v[68:69], off nt
	v_lshl_add_u64 v[36:37], v[28:29], 0, v[70:71]
	v_lshlrev_b64 v[38:39], 12, v[6:7]
	v_or_b32_e32 v6, s53, v30
	s_add_i32 s57, s43, 28
	v_lshl_add_u64 v[34:35], v[28:29], 0, v[74:75]
	global_load_dword v94, v[36:37], off nt
	global_load_dword v95, v[34:35], off nt
	v_lshlrev_b64 v[36:37], 12, v[6:7]
	v_or_b32_e32 v6, s55, v30
	v_lshl_add_u64 v[34:35], v[28:29], 0, v[38:39]
	v_lshlrev_b64 v[38:39], 12, v[6:7]
	v_or_b32_e32 v6, s57, v30
	v_lshlrev_b64 v[40:41], 12, v[6:7]
	v_lshl_add_u64 v[40:41], v[28:29], 0, v[40:41]
	v_lshl_add_u64 v[36:37], v[28:29], 0, v[36:37]
	v_lshl_add_u64 v[38:39], v[28:29], 0, v[38:39]
	global_load_dword v6, v[40:41], off nt
	global_load_dword v96, v[38:39], off nt
	global_load_dword v97, v[36:37], off nt
	global_load_dword v98, v[34:35], off nt
	v_or_b32_e32 v36, s42, v1
	v_or_b32_e32 v34, s43, v2
	s_add_i32 s40, s40, 16
	s_add_i32 s39, s39, 16
	s_add_i32 s41, s41, -16
	v_mad_u64_u32 v[34:35], s[42:43], v34, s25, v[4:5]
	v_mad_u64_u32 v[36:37], s[42:43], v36, s25, v[4:5]
	v_or_b32_e32 v35, s44, v1
	v_or_b32_e32 v37, s45, v2
	v_or_b32_e32 v44, s46, v1
	v_or_b32_e32 v42, s47, v2
	v_or_b32_e32 v68, s48, v1
	v_or_b32_e32 v66, s49, v2
	v_or_b32_e32 v72, s50, v1
	v_or_b32_e32 v70, s51, v2
	v_or_b32_e32 v76, s52, v1
	v_or_b32_e32 v74, s53, v2
	v_or_b32_e32 v80, s54, v1
	v_or_b32_e32 v78, s55, v2
	v_or_b32_e32 v84, s56, v1
	v_or_b32_e32 v82, s57, v2
	s_cmp_lg_u32 s41, 0
	v_mad_u64_u32 v[38:39], s[42:43], v37, s25, v[4:5]
	v_mad_u64_u32 v[40:41], s[42:43], v35, s25, v[4:5]
	v_mad_u64_u32 v[42:43], s[42:43], v42, s25, v[4:5]
	v_mad_u64_u32 v[44:45], s[42:43], v44, s25, v[4:5]
	v_mad_u64_u32 v[66:67], s[42:43], v66, s25, v[4:5]
	v_mad_u64_u32 v[68:69], s[42:43], v68, s25, v[4:5]
	v_mad_u64_u32 v[70:71], s[42:43], v70, s25, v[4:5]
	v_mad_u64_u32 v[72:73], s[42:43], v72, s25, v[4:5]
	v_mad_u64_u32 v[74:75], s[42:43], v74, s25, v[4:5]
	v_mad_u64_u32 v[76:77], s[42:43], v76, s25, v[4:5]
	v_mad_u64_u32 v[78:79], s[42:43], v78, s25, v[4:5]
	v_mad_u64_u32 v[80:81], s[42:43], v80, s25, v[4:5]
	v_mad_u64_u32 v[82:83], s[42:43], v82, s25, v[4:5]
	v_mad_u64_u32 v[84:85], s[42:43], v84, s25, v[4:5]
	s_waitcnt vmcnt(15)
	ds_write_b32 v34, v33
	s_waitcnt vmcnt(14)
	ds_write_b32 v36, v65
	s_waitcnt vmcnt(13)
	ds_write_b32 v38, v86
	s_waitcnt vmcnt(12)
	ds_write_b32 v40, v87
	s_waitcnt vmcnt(4)
	ds_write_b32 v42, v95
	ds_write_b32 v44, v88
	ds_write_b32 v66, v94
	ds_write_b32 v68, v89
	s_waitcnt vmcnt(0)
	ds_write_b32 v70, v98
	ds_write_b32 v72, v90
	ds_write_b32 v74, v97
	ds_write_b32 v76, v91
	ds_write_b32 v78, v96
	ds_write_b32 v80, v92
	ds_write_b32 v82, v6
	ds_write_b32 v84, v93
	s_cbranch_scc1 .LBB0_93
	s_waitcnt lgkmcnt(0)
	ds_read2_b32 v[28:29], v48 offset1:33
	s_waitcnt lgkmcnt(0)
	v_cvt_pk_bf16_f32 v34, v28, v29
	ds_read2_b32 v[28:29], v48 offset0:66 offset1:99
	s_waitcnt lgkmcnt(0)
	v_cvt_pk_bf16_f32 v35, v28, v29
	ds_read2_b32 v[28:29], v48 offset0:132 offset1:165
	v_lshlrev_b32_e32 v6, 1, v32
	v_or_b32_e32 v3, v31, v47
	s_waitcnt lgkmcnt(0)
	v_cvt_pk_bf16_f32 v36, v28, v29
	ds_read2_b32 v[28:29], v48 offset0:198 offset1:231
	v_lshl_add_u64 v[38:39], v[10:11], 0, v[6:7]
	v_lshlrev_b32_e32 v6, 12, v3
	s_waitcnt lgkmcnt(0)
	v_cvt_pk_bf16_f32 v37, v28, v29
	ds_read2_b32 v[28:29], v48 offset0:8 offset1:41
	v_lshl_add_u64 v[32:33], v[38:39], 0, v[6:7]
	global_store_dwordx4 v[32:33], v[34:37], off
	s_waitcnt lgkmcnt(0)
	v_cvt_pk_bf16_f32 v32, v28, v29
	ds_read2_b32 v[28:29], v48 offset0:74 offset1:107
	s_waitcnt lgkmcnt(0)
	v_cvt_pk_bf16_f32 v33, v28, v29
	ds_read2_b32 v[28:29], v48 offset0:140 offset1:173
	v_or_b32_e32 v3, v31, v49
	s_waitcnt lgkmcnt(0)
	v_cvt_pk_bf16_f32 v34, v28, v29
	ds_read2_b32 v[28:29], v48 offset0:206 offset1:239
	v_lshlrev_b32_e32 v6, 12, v3
	s_waitcnt lgkmcnt(0)
	v_cvt_pk_bf16_f32 v35, v28, v29
	ds_read2_b32 v[28:29], v48 offset0:16 offset1:49
	v_lshl_add_u64 v[36:37], v[38:39], 0, v[6:7]
	global_store_dwordx4 v[36:37], v[32:35], off
	v_or_b32_e32 v3, v31, v50
	v_lshlrev_b32_e32 v6, 12, v3
	s_waitcnt lgkmcnt(0)
	v_cvt_pk_bf16_f32 v32, v28, v29
	ds_read2_b32 v[28:29], v48 offset0:82 offset1:115
	s_waitcnt lgkmcnt(0)
	v_cvt_pk_bf16_f32 v33, v28, v29
	ds_read2_b32 v[28:29], v48 offset0:148 offset1:181
	s_waitcnt lgkmcnt(0)
	v_cvt_pk_bf16_f32 v34, v28, v29
	ds_read2_b32 v[28:29], v48 offset0:214 offset1:247
	s_waitcnt lgkmcnt(0)
	v_cvt_pk_bf16_f32 v35, v28, v29
	ds_read2_b32 v[28:29], v48 offset0:24 offset1:57
	v_lshl_add_u64 v[36:37], v[38:39], 0, v[6:7]
	global_store_dwordx4 v[36:37], v[32:35], off
	s_waitcnt lgkmcnt(0)
	v_cvt_pk_bf16_f32 v28, v28, v29
	ds_read2_b32 v[32:33], v48 offset0:90 offset1:123
	s_waitcnt lgkmcnt(0)
	v_cvt_pk_bf16_f32 v29, v32, v33
	ds_read2_b32 v[32:33], v48 offset0:156 offset1:189
	v_or_b32_e32 v3, v31, v51
	s_waitcnt lgkmcnt(0)
	v_cvt_pk_bf16_f32 v30, v32, v33
	ds_read2_b32 v[32:33], v48 offset0:222 offset1:255
	v_lshlrev_b32_e32 v6, 12, v3
	s_waitcnt lgkmcnt(0)
	v_cvt_pk_bf16_f32 v31, v32, v33
	v_lshl_add_u64 v[32:33], v[38:39], 0, v[6:7]
	global_store_dwordx4 v[32:33], v[28:31], off
	s_waitcnt lgkmcnt(0)

.LBB0_98:
	s_lshl_b32 s41, s27, 1
	s_lshl_b32 s40, s26, 1
	v_or_b32_e32 v6, s41, v30
	s_add_i32 s43, s41, 4
	s_add_i32 s42, s40, 4
	s_add_i32 s44, s40, 8
	s_add_i32 s45, s41, 8
	v_lshlrev_b64 v[70:71], 14, v[6:7]
	v_or_b32_e32 v6, s43, v30
	v_mov_b32_e32 v35, v7
	v_mov_b32_e32 v37, v7
	v_mov_b32_e32 v39, v7
	v_or_b32_e32 v34, s40, v3
	s_add_i32 s46, s40, 12
	s_add_i32 s47, s41, 12
	s_add_i32 s48, s40, 16
	s_add_i32 s50, s40, 20
	s_add_i32 s52, s40, 24
	s_add_i32 s54, s40, 28
	v_or_b32_e32 v36, s42, v3
	v_or_b32_e32 v38, s44, v3
	v_lshlrev_b64 v[72:73], 14, v[6:7]
	v_or_b32_e32 v6, s45, v30
	v_mov_b32_e32 v41, v7
	v_mov_b32_e32 v43, v7
	v_mov_b32_e32 v45, v7
	v_mov_b32_e32 v67, v7
	v_mov_b32_e32 v69, v7
	s_add_i32 s49, s41, 16
	v_lshlrev_b64 v[34:35], 14, v[34:35]
	v_or_b32_e32 v40, s46, v3
	v_or_b32_e32 v42, s48, v3
	v_or_b32_e32 v44, s50, v3
	v_or_b32_e32 v66, s52, v3
	v_or_b32_e32 v68, s54, v3
	v_lshl_add_u64 v[70:71], v[28:29], 0, v[70:71]
	v_lshlrev_b64 v[36:37], 14, v[36:37]
	v_lshlrev_b64 v[38:39], 14, v[38:39]
	v_lshlrev_b64 v[74:75], 14, v[6:7]
	v_or_b32_e32 v6, s47, v30
	s_add_i32 s51, s41, 20
	v_lshl_add_u64 v[34:35], v[28:29], 0, v[34:35]
	v_lshlrev_b64 v[40:41], 14, v[40:41]
	v_lshlrev_b64 v[42:43], 14, v[42:43]
	v_lshlrev_b64 v[44:45], 14, v[44:45]
	v_lshlrev_b64 v[66:67], 14, v[66:67]
	v_lshlrev_b64 v[68:69], 14, v[68:69]
	v_lshl_add_u64 v[72:73], v[28:29], 0, v[72:73]
	v_lshl_add_u64 v[36:37], v[28:29], 0, v[36:37]
	v_lshl_add_u64 v[38:39], v[28:29], 0, v[38:39]
	global_load_dword v33, v[70:71], off nt
	global_load_dword v65, v[34:35], off nt
	v_lshlrev_b64 v[70:71], 14, v[6:7]
	v_or_b32_e32 v6, s49, v30
	s_add_i32 s53, s41, 24
	v_lshl_add_u64 v[40:41], v[28:29], 0, v[40:41]
	v_lshl_add_u64 v[42:43], v[28:29], 0, v[42:43]
	v_lshl_add_u64 v[44:45], v[28:29], 0, v[44:45]
	v_lshl_add_u64 v[66:67], v[28:29], 0, v[66:67]
	v_lshl_add_u64 v[68:69], v[28:29], 0, v[68:69]
	global_load_dword v86, v[72:73], off nt
	global_load_dword v87, v[36:37], off nt
	global_load_dword v88, v[38:39], off nt
	global_load_dword v89, v[40:41], off nt
	global_load_dword v90, v[42:43], off nt
	global_load_dword v91, v[44:45], off nt
	global_load_dword v92, v[66:67], off nt
	global_load_dword v93, v[68:69], off nt
	v_lshl_add_u64 v[36:37], v[28:29], 0, v[70:71]
	v_lshlrev_b64 v[38:39], 14, v[6:7]
	v_or_b32_e32 v6, s51, v30
	s_add_i32 s55, s41, 28
	v_lshl_add_u64 v[34:35], v[28:29], 0, v[74:75]
	global_load_dword v94, v[36:37], off nt
	global_load_dword v95, v[34:35], off nt
	v_lshlrev_b64 v[36:37], 14, v[6:7]
	v_or_b32_e32 v6, s53, v30
	v_lshl_add_u64 v[34:35], v[28:29], 0, v[38:39]
	v_lshlrev_b64 v[38:39], 14, v[6:7]
	v_or_b32_e32 v6, s55, v30
	v_lshlrev_b64 v[40:41], 14, v[6:7]
	v_lshl_add_u64 v[40:41], v[28:29], 0, v[40:41]
	v_lshl_add_u64 v[36:37], v[28:29], 0, v[36:37]
	v_lshl_add_u64 v[38:39], v[28:29], 0, v[38:39]
	global_load_dword v6, v[40:41], off nt
	global_load_dword v96, v[38:39], off nt
	global_load_dword v97, v[36:37], off nt
	global_load_dword v98, v[34:35], off nt
	v_or_b32_e32 v36, s40, v1
	v_or_b32_e32 v34, s41, v2
	s_add_i32 s27, s27, 16
	s_add_i32 s26, s26, 16
	s_add_i32 s39, s39, -16
	v_mad_u64_u32 v[34:35], s[40:41], v34, s25, v[4:5]
	v_mad_u64_u32 v[36:37], s[40:41], v36, s25, v[4:5]
	v_or_b32_e32 v35, s42, v1
	v_or_b32_e32 v37, s43, v2
	v_or_b32_e32 v44, s44, v1
	v_or_b32_e32 v42, s45, v2
	v_or_b32_e32 v68, s46, v1
	v_or_b32_e32 v66, s47, v2
	v_or_b32_e32 v72, s48, v1
	v_or_b32_e32 v70, s49, v2
	v_or_b32_e32 v76, s50, v1
	v_or_b32_e32 v74, s51, v2
	v_or_b32_e32 v80, s52, v1
	v_or_b32_e32 v78, s53, v2
	v_or_b32_e32 v84, s54, v1
	v_or_b32_e32 v82, s55, v2
	s_cmp_lg_u32 s39, 0
	v_mad_u64_u32 v[38:39], s[40:41], v37, s25, v[4:5]
	v_mad_u64_u32 v[40:41], s[40:41], v35, s25, v[4:5]
	v_mad_u64_u32 v[42:43], s[40:41], v42, s25, v[4:5]
	v_mad_u64_u32 v[44:45], s[40:41], v44, s25, v[4:5]
	v_mad_u64_u32 v[66:67], s[40:41], v66, s25, v[4:5]
	v_mad_u64_u32 v[68:69], s[40:41], v68, s25, v[4:5]
	v_mad_u64_u32 v[70:71], s[40:41], v70, s25, v[4:5]
	v_mad_u64_u32 v[72:73], s[40:41], v72, s25, v[4:5]
	v_mad_u64_u32 v[74:75], s[40:41], v74, s25, v[4:5]
	v_mad_u64_u32 v[76:77], s[40:41], v76, s25, v[4:5]
	v_mad_u64_u32 v[78:79], s[40:41], v78, s25, v[4:5]
	v_mad_u64_u32 v[80:81], s[40:41], v80, s25, v[4:5]
	v_mad_u64_u32 v[82:83], s[40:41], v82, s25, v[4:5]
	v_mad_u64_u32 v[84:85], s[40:41], v84, s25, v[4:5]
	s_waitcnt vmcnt(15)
	ds_write_b32 v34, v33
	s_waitcnt vmcnt(14)
	ds_write_b32 v36, v65
	s_waitcnt vmcnt(13)
	ds_write_b32 v38, v86
	s_waitcnt vmcnt(12)
	ds_write_b32 v40, v87
	s_waitcnt vmcnt(4)
	ds_write_b32 v42, v95
	ds_write_b32 v44, v88
	ds_write_b32 v66, v94
	ds_write_b32 v68, v89
	s_waitcnt vmcnt(0)
	ds_write_b32 v70, v98
	ds_write_b32 v72, v90
	ds_write_b32 v74, v97
	ds_write_b32 v76, v91
	ds_write_b32 v78, v96
	ds_write_b32 v80, v92
	ds_write_b32 v82, v6
	ds_write_b32 v84, v93
	s_cbranch_scc1 .LBB0_98
	s_waitcnt lgkmcnt(0)
	ds_read2_b32 v[28:29], v48 offset1:33
	s_waitcnt lgkmcnt(0)
	v_cvt_pk_bf16_f32 v34, v28, v29
	ds_read2_b32 v[28:29], v48 offset0:66 offset1:99
	s_waitcnt lgkmcnt(0)
	v_cvt_pk_bf16_f32 v35, v28, v29
	ds_read2_b32 v[28:29], v48 offset0:132 offset1:165
	v_lshlrev_b32_e32 v6, 1, v32
	v_or_b32_e32 v3, v31, v47
	s_waitcnt lgkmcnt(0)
	v_cvt_pk_bf16_f32 v36, v28, v29
	ds_read2_b32 v[28:29], v48 offset0:198 offset1:231
	v_lshl_add_u64 v[38:39], v[12:13], 0, v[6:7]
	v_lshlrev_b32_e32 v6, 11, v3
	s_waitcnt lgkmcnt(0)
	v_cvt_pk_bf16_f32 v37, v28, v29
	ds_read2_b32 v[28:29], v48 offset0:8 offset1:41
	v_lshl_add_u64 v[32:33], v[38:39], 0, v[6:7]
	global_store_dwordx4 v[32:33], v[34:37], off
	s_waitcnt lgkmcnt(0)
	v_cvt_pk_bf16_f32 v32, v28, v29
	ds_read2_b32 v[28:29], v48 offset0:74 offset1:107
	s_waitcnt lgkmcnt(0)
	v_cvt_pk_bf16_f32 v33, v28, v29
	ds_read2_b32 v[28:29], v48 offset0:140 offset1:173
	v_or_b32_e32 v3, v31, v49
	s_waitcnt lgkmcnt(0)
	v_cvt_pk_bf16_f32 v34, v28, v29
	ds_read2_b32 v[28:29], v48 offset0:206 offset1:239
	v_lshlrev_b32_e32 v6, 11, v3
	s_waitcnt lgkmcnt(0)
	v_cvt_pk_bf16_f32 v35, v28, v29
	ds_read2_b32 v[28:29], v48 offset0:16 offset1:49
	v_lshl_add_u64 v[36:37], v[38:39], 0, v[6:7]
	global_store_dwordx4 v[36:37], v[32:35], off
	v_or_b32_e32 v3, v31, v50
	v_lshlrev_b32_e32 v6, 11, v3
	s_waitcnt lgkmcnt(0)
	v_cvt_pk_bf16_f32 v32, v28, v29
	ds_read2_b32 v[28:29], v48 offset0:82 offset1:115
	s_waitcnt lgkmcnt(0)
	v_cvt_pk_bf16_f32 v33, v28, v29
	ds_read2_b32 v[28:29], v48 offset0:148 offset1:181
	s_waitcnt lgkmcnt(0)
	v_cvt_pk_bf16_f32 v34, v28, v29
	ds_read2_b32 v[28:29], v48 offset0:214 offset1:247
	s_waitcnt lgkmcnt(0)
	v_cvt_pk_bf16_f32 v35, v28, v29
	ds_read2_b32 v[28:29], v48 offset0:24 offset1:57
	v_lshl_add_u64 v[36:37], v[38:39], 0, v[6:7]
	global_store_dwordx4 v[36:37], v[32:35], off
	s_waitcnt lgkmcnt(0)
	v_cvt_pk_bf16_f32 v28, v28, v29
	ds_read2_b32 v[32:33], v48 offset0:90 offset1:123
	s_waitcnt lgkmcnt(0)
	v_cvt_pk_bf16_f32 v29, v32, v33
	ds_read2_b32 v[32:33], v48 offset0:156 offset1:189
	v_or_b32_e32 v3, v31, v51
	s_waitcnt lgkmcnt(0)
	v_cvt_pk_bf16_f32 v30, v32, v33
	ds_read2_b32 v[32:33], v48 offset0:222 offset1:255
	v_lshlrev_b32_e32 v6, 11, v3
	s_waitcnt lgkmcnt(0)
	v_cvt_pk_bf16_f32 v31, v32, v33
	v_lshl_add_u64 v[32:33], v[38:39], 0, v[6:7]
	global_store_dwordx4 v[32:33], v[28:31], off
	s_waitcnt lgkmcnt(0)

.LBB0_103:
	s_lshl_b32 s39, s23, 1
	s_lshl_b32 s27, s22, 1
	v_or_b32_e32 v6, s39, v30
	s_add_i32 s43, s39, 4
	s_add_i32 s42, s27, 4
	s_add_i32 s44, s27, 8
	s_add_i32 s45, s39, 8
	v_lshlrev_b64 v[70:71], 12, v[6:7]
	v_or_b32_e32 v6, s43, v30
	v_mov_b32_e32 v35, v7
	v_mov_b32_e32 v37, v7
	v_mov_b32_e32 v39, v7
	v_or_b32_e32 v34, s27, v3
	s_add_i32 s46, s27, 12
	s_add_i32 s47, s39, 12
	s_add_i32 s48, s27, 16
	s_add_i32 s50, s27, 20
	s_add_i32 s52, s27, 24
	s_add_i32 s54, s27, 28
	v_or_b32_e32 v36, s42, v3
	v_or_b32_e32 v38, s44, v3
	v_lshlrev_b64 v[72:73], 12, v[6:7]
	v_or_b32_e32 v6, s45, v30
	v_mov_b32_e32 v41, v7
	v_mov_b32_e32 v43, v7
	v_mov_b32_e32 v45, v7
	v_mov_b32_e32 v67, v7
	v_mov_b32_e32 v69, v7
	s_add_i32 s49, s39, 16
	v_lshlrev_b64 v[34:35], 12, v[34:35]
	v_or_b32_e32 v40, s46, v3
	v_or_b32_e32 v42, s48, v3
	v_or_b32_e32 v44, s50, v3
	v_or_b32_e32 v66, s52, v3
	v_or_b32_e32 v68, s54, v3
	v_lshl_add_u64 v[70:71], v[28:29], 0, v[70:71]
	v_lshlrev_b64 v[36:37], 12, v[36:37]
	v_lshlrev_b64 v[38:39], 12, v[38:39]
	v_lshlrev_b64 v[74:75], 12, v[6:7]
	v_or_b32_e32 v6, s47, v30
	s_add_i32 s51, s39, 20
	v_lshl_add_u64 v[34:35], v[28:29], 0, v[34:35]
	v_lshlrev_b64 v[40:41], 12, v[40:41]
	v_lshlrev_b64 v[42:43], 12, v[42:43]
	v_lshlrev_b64 v[44:45], 12, v[44:45]
	v_lshlrev_b64 v[66:67], 12, v[66:67]
	v_lshlrev_b64 v[68:69], 12, v[68:69]
	v_lshl_add_u64 v[72:73], v[28:29], 0, v[72:73]
	v_lshl_add_u64 v[36:37], v[28:29], 0, v[36:37]
	v_lshl_add_u64 v[38:39], v[28:29], 0, v[38:39]
	global_load_dword v33, v[70:71], off nt
	global_load_dword v65, v[34:35], off nt
	v_lshlrev_b64 v[70:71], 12, v[6:7]
	v_or_b32_e32 v6, s49, v30
	s_add_i32 s53, s39, 24
	v_lshl_add_u64 v[40:41], v[28:29], 0, v[40:41]
	v_lshl_add_u64 v[42:43], v[28:29], 0, v[42:43]
	v_lshl_add_u64 v[44:45], v[28:29], 0, v[44:45]
	v_lshl_add_u64 v[66:67], v[28:29], 0, v[66:67]
	v_lshl_add_u64 v[68:69], v[28:29], 0, v[68:69]
	global_load_dword v86, v[72:73], off nt
	global_load_dword v87, v[36:37], off nt
	global_load_dword v88, v[38:39], off nt
	global_load_dword v89, v[40:41], off nt
	global_load_dword v90, v[42:43], off nt
	global_load_dword v91, v[44:45], off nt
	global_load_dword v92, v[66:67], off nt
	global_load_dword v93, v[68:69], off nt
	v_lshl_add_u64 v[36:37], v[28:29], 0, v[70:71]
	v_lshlrev_b64 v[38:39], 12, v[6:7]
	v_or_b32_e32 v6, s51, v30
	s_add_i32 s55, s39, 28
	v_lshl_add_u64 v[34:35], v[28:29], 0, v[74:75]
	global_load_dword v94, v[36:37], off nt
	global_load_dword v95, v[34:35], off nt
	v_lshlrev_b64 v[36:37], 12, v[6:7]
	v_or_b32_e32 v6, s53, v30
	v_lshl_add_u64 v[34:35], v[28:29], 0, v[38:39]
	v_lshlrev_b64 v[38:39], 12, v[6:7]
	v_or_b32_e32 v6, s55, v30
	v_lshlrev_b64 v[40:41], 12, v[6:7]
	v_lshl_add_u64 v[40:41], v[28:29], 0, v[40:41]
	v_lshl_add_u64 v[36:37], v[28:29], 0, v[36:37]
	v_lshl_add_u64 v[38:39], v[28:29], 0, v[38:39]
	global_load_dword v6, v[40:41], off nt
	global_load_dword v96, v[38:39], off nt
	global_load_dword v97, v[36:37], off nt
	global_load_dword v98, v[34:35], off nt
	v_or_b32_e32 v36, s27, v1
	v_or_b32_e32 v34, s39, v2
	s_add_i32 s23, s23, 16
	s_add_i32 s22, s22, 16
	s_add_i32 s26, s26, -16
	v_mad_u64_u32 v[34:35], s[40:41], v34, s25, v[4:5]
	v_mad_u64_u32 v[36:37], s[40:41], v36, s25, v[4:5]
	v_or_b32_e32 v35, s42, v1
	v_or_b32_e32 v37, s43, v2
	v_or_b32_e32 v44, s44, v1
	v_or_b32_e32 v42, s45, v2
	v_or_b32_e32 v68, s46, v1
	v_or_b32_e32 v66, s47, v2
	v_or_b32_e32 v72, s48, v1
	v_or_b32_e32 v70, s49, v2
	v_or_b32_e32 v76, s50, v1
	v_or_b32_e32 v74, s51, v2
	v_or_b32_e32 v80, s52, v1
	v_or_b32_e32 v78, s53, v2
	v_or_b32_e32 v84, s54, v1
	v_or_b32_e32 v82, s55, v2
	s_cmp_lg_u32 s26, 0
	v_mad_u64_u32 v[38:39], s[40:41], v37, s25, v[4:5]
	v_mad_u64_u32 v[40:41], s[40:41], v35, s25, v[4:5]
	v_mad_u64_u32 v[42:43], s[40:41], v42, s25, v[4:5]
	v_mad_u64_u32 v[44:45], s[40:41], v44, s25, v[4:5]
	v_mad_u64_u32 v[66:67], s[40:41], v66, s25, v[4:5]
	v_mad_u64_u32 v[68:69], s[40:41], v68, s25, v[4:5]
	v_mad_u64_u32 v[70:71], s[40:41], v70, s25, v[4:5]
	v_mad_u64_u32 v[72:73], s[40:41], v72, s25, v[4:5]
	v_mad_u64_u32 v[74:75], s[40:41], v74, s25, v[4:5]
	v_mad_u64_u32 v[76:77], s[40:41], v76, s25, v[4:5]
	v_mad_u64_u32 v[78:79], s[40:41], v78, s25, v[4:5]
	v_mad_u64_u32 v[80:81], s[40:41], v80, s25, v[4:5]
	v_mad_u64_u32 v[82:83], s[40:41], v82, s25, v[4:5]
	v_mad_u64_u32 v[84:85], s[40:41], v84, s25, v[4:5]
	s_waitcnt vmcnt(15)
	ds_write_b32 v34, v33
	s_waitcnt vmcnt(14)
	ds_write_b32 v36, v65
	s_waitcnt vmcnt(13)
	ds_write_b32 v38, v86
	s_waitcnt vmcnt(12)
	ds_write_b32 v40, v87
	s_waitcnt vmcnt(4)
	ds_write_b32 v42, v95
	ds_write_b32 v44, v88
	ds_write_b32 v66, v94
	ds_write_b32 v68, v89
	s_waitcnt vmcnt(0)
	ds_write_b32 v70, v98
	ds_write_b32 v72, v90
	ds_write_b32 v74, v97
	ds_write_b32 v76, v91
	ds_write_b32 v78, v96
	ds_write_b32 v80, v92
	ds_write_b32 v82, v6
	ds_write_b32 v84, v93
	s_cbranch_scc1 .LBB0_103
	s_waitcnt lgkmcnt(0)
	ds_read2_b32 v[28:29], v48 offset1:33
	s_waitcnt lgkmcnt(0)
	v_cvt_pk_bf16_f32 v34, v28, v29
	ds_read2_b32 v[28:29], v48 offset0:66 offset1:99
	s_waitcnt lgkmcnt(0)
	v_cvt_pk_bf16_f32 v35, v28, v29
	ds_read2_b32 v[28:29], v48 offset0:132 offset1:165
	v_lshlrev_b32_e32 v6, 1, v32
	v_or_b32_e32 v3, v31, v47
	s_waitcnt lgkmcnt(0)
	v_cvt_pk_bf16_f32 v36, v28, v29
	ds_read2_b32 v[28:29], v48 offset0:198 offset1:231
	v_lshl_add_u64 v[38:39], v[14:15], 0, v[6:7]
	v_lshlrev_b32_e32 v6, 11, v3
	s_waitcnt lgkmcnt(0)
	v_cvt_pk_bf16_f32 v37, v28, v29
	ds_read2_b32 v[28:29], v48 offset0:8 offset1:41
	v_lshl_add_u64 v[32:33], v[38:39], 0, v[6:7]
	global_store_dwordx4 v[32:33], v[34:37], off
	s_waitcnt lgkmcnt(0)
	v_cvt_pk_bf16_f32 v32, v28, v29
	ds_read2_b32 v[28:29], v48 offset0:74 offset1:107
	s_waitcnt lgkmcnt(0)
	v_cvt_pk_bf16_f32 v33, v28, v29
	ds_read2_b32 v[28:29], v48 offset0:140 offset1:173
	v_or_b32_e32 v3, v31, v49
	s_waitcnt lgkmcnt(0)
	v_cvt_pk_bf16_f32 v34, v28, v29
	ds_read2_b32 v[28:29], v48 offset0:206 offset1:239
	v_lshlrev_b32_e32 v6, 11, v3
	s_waitcnt lgkmcnt(0)
	v_cvt_pk_bf16_f32 v35, v28, v29
	ds_read2_b32 v[28:29], v48 offset0:16 offset1:49
	v_lshl_add_u64 v[36:37], v[38:39], 0, v[6:7]
	global_store_dwordx4 v[36:37], v[32:35], off
	v_or_b32_e32 v3, v31, v50
	v_lshlrev_b32_e32 v6, 11, v3
	s_waitcnt lgkmcnt(0)
	v_cvt_pk_bf16_f32 v32, v28, v29
	ds_read2_b32 v[28:29], v48 offset0:82 offset1:115
	s_waitcnt lgkmcnt(0)
	v_cvt_pk_bf16_f32 v33, v28, v29
	ds_read2_b32 v[28:29], v48 offset0:148 offset1:181
	s_waitcnt lgkmcnt(0)
	v_cvt_pk_bf16_f32 v34, v28, v29
	ds_read2_b32 v[28:29], v48 offset0:214 offset1:247
	s_waitcnt lgkmcnt(0)
	v_cvt_pk_bf16_f32 v35, v28, v29
	ds_read2_b32 v[28:29], v48 offset0:24 offset1:57
	v_lshl_add_u64 v[36:37], v[38:39], 0, v[6:7]
	global_store_dwordx4 v[36:37], v[32:35], off
	s_waitcnt lgkmcnt(0)
	v_cvt_pk_bf16_f32 v28, v28, v29
	ds_read2_b32 v[32:33], v48 offset0:90 offset1:123
	s_waitcnt lgkmcnt(0)
	v_cvt_pk_bf16_f32 v29, v32, v33
	ds_read2_b32 v[32:33], v48 offset0:156 offset1:189
	v_or_b32_e32 v3, v31, v51
	s_waitcnt lgkmcnt(0)
	v_cvt_pk_bf16_f32 v30, v32, v33
	ds_read2_b32 v[32:33], v48 offset0:222 offset1:255
	v_lshlrev_b32_e32 v6, 11, v3
	s_waitcnt lgkmcnt(0)
	v_cvt_pk_bf16_f32 v31, v32, v33
	v_lshl_add_u64 v[32:33], v[38:39], 0, v[6:7]
	global_store_dwordx4 v[32:33], v[28:31], off
	s_waitcnt lgkmcnt(0)

.LBB0_108:
	s_lshl_b32 s26, s21, 1
	s_lshl_b32 s23, s20, 1
	v_or_b32_e32 v6, s26, v30
	s_add_i32 s40, s26, 4
	s_add_i32 s39, s23, 4
	s_add_i32 s41, s23, 8
	s_add_i32 s42, s26, 8
	v_lshlrev_b64 v[70:71], 12, v[6:7]
	v_or_b32_e32 v6, s40, v30
	v_mov_b32_e32 v35, v7
	v_mov_b32_e32 v37, v7
	v_mov_b32_e32 v39, v7
	v_or_b32_e32 v34, s23, v3
	s_add_i32 s43, s23, 12
	s_add_i32 s44, s26, 12
	s_add_i32 s45, s23, 16
	s_add_i32 s47, s23, 20
	s_add_i32 s49, s23, 24
	s_add_i32 s51, s23, 28
	v_or_b32_e32 v36, s39, v3
	v_or_b32_e32 v38, s41, v3
	v_lshlrev_b64 v[72:73], 12, v[6:7]
	v_or_b32_e32 v6, s42, v30
	v_mov_b32_e32 v41, v7
	v_mov_b32_e32 v43, v7
	v_mov_b32_e32 v45, v7
	v_mov_b32_e32 v67, v7
	v_mov_b32_e32 v69, v7
	s_add_i32 s46, s26, 16
	v_lshlrev_b64 v[34:35], 12, v[34:35]
	v_or_b32_e32 v40, s43, v3
	v_or_b32_e32 v42, s45, v3
	v_or_b32_e32 v44, s47, v3
	v_or_b32_e32 v66, s49, v3
	v_or_b32_e32 v68, s51, v3
	v_lshl_add_u64 v[70:71], v[28:29], 0, v[70:71]
	v_lshlrev_b64 v[36:37], 12, v[36:37]
	v_lshlrev_b64 v[38:39], 12, v[38:39]
	v_lshlrev_b64 v[74:75], 12, v[6:7]
	v_or_b32_e32 v6, s44, v30
	s_add_i32 s48, s26, 20
	v_lshl_add_u64 v[34:35], v[28:29], 0, v[34:35]
	v_lshlrev_b64 v[40:41], 12, v[40:41]
	v_lshlrev_b64 v[42:43], 12, v[42:43]
	v_lshlrev_b64 v[44:45], 12, v[44:45]
	v_lshlrev_b64 v[66:67], 12, v[66:67]
	v_lshlrev_b64 v[68:69], 12, v[68:69]
	v_lshl_add_u64 v[72:73], v[28:29], 0, v[72:73]
	v_lshl_add_u64 v[36:37], v[28:29], 0, v[36:37]
	v_lshl_add_u64 v[38:39], v[28:29], 0, v[38:39]
	global_load_dword v33, v[70:71], off nt
	global_load_dword v65, v[34:35], off nt
	v_lshlrev_b64 v[70:71], 12, v[6:7]
	v_or_b32_e32 v6, s46, v30
	s_add_i32 s50, s26, 24
	v_lshl_add_u64 v[40:41], v[28:29], 0, v[40:41]
	v_lshl_add_u64 v[42:43], v[28:29], 0, v[42:43]
	v_lshl_add_u64 v[44:45], v[28:29], 0, v[44:45]
	v_lshl_add_u64 v[66:67], v[28:29], 0, v[66:67]
	v_lshl_add_u64 v[68:69], v[28:29], 0, v[68:69]
	global_load_dword v86, v[72:73], off nt
	global_load_dword v87, v[36:37], off nt
	global_load_dword v88, v[38:39], off nt
	global_load_dword v89, v[40:41], off nt
	global_load_dword v90, v[42:43], off nt
	global_load_dword v91, v[44:45], off nt
	global_load_dword v92, v[66:67], off nt
	global_load_dword v93, v[68:69], off nt
	v_lshl_add_u64 v[36:37], v[28:29], 0, v[70:71]
	v_lshlrev_b64 v[38:39], 12, v[6:7]
	v_or_b32_e32 v6, s48, v30
	s_add_i32 s52, s26, 28
	v_lshl_add_u64 v[34:35], v[28:29], 0, v[74:75]
	global_load_dword v94, v[36:37], off nt
	global_load_dword v95, v[34:35], off nt
	v_lshlrev_b64 v[36:37], 12, v[6:7]
	v_or_b32_e32 v6, s50, v30
	v_lshl_add_u64 v[34:35], v[28:29], 0, v[38:39]
	v_lshlrev_b64 v[38:39], 12, v[6:7]
	v_or_b32_e32 v6, s52, v30
	v_lshlrev_b64 v[40:41], 12, v[6:7]
	v_lshl_add_u64 v[40:41], v[28:29], 0, v[40:41]
	v_lshl_add_u64 v[36:37], v[28:29], 0, v[36:37]
	v_lshl_add_u64 v[38:39], v[28:29], 0, v[38:39]
	global_load_dword v6, v[40:41], off nt
	global_load_dword v96, v[38:39], off nt
	global_load_dword v97, v[36:37], off nt
	global_load_dword v98, v[34:35], off nt
	v_or_b32_e32 v36, s23, v1
	v_or_b32_e32 v34, s26, v2
	s_add_i32 s21, s21, 16
	s_add_i32 s20, s20, 16
	s_add_i32 s22, s22, -16
	v_mad_u64_u32 v[34:35], s[26:27], v34, s25, v[4:5]
	v_mad_u64_u32 v[36:37], s[26:27], v36, s25, v[4:5]
	v_or_b32_e32 v35, s39, v1
	v_or_b32_e32 v37, s40, v2
	v_or_b32_e32 v44, s41, v1
	v_or_b32_e32 v42, s42, v2
	v_or_b32_e32 v68, s43, v1
	v_or_b32_e32 v66, s44, v2
	v_or_b32_e32 v72, s45, v1
	v_or_b32_e32 v70, s46, v2
	v_or_b32_e32 v76, s47, v1
	v_or_b32_e32 v74, s48, v2
	v_or_b32_e32 v80, s49, v1
	v_or_b32_e32 v78, s50, v2
	v_or_b32_e32 v84, s51, v1
	v_or_b32_e32 v82, s52, v2
	s_cmp_lg_u32 s22, 0
	v_mad_u64_u32 v[38:39], s[26:27], v37, s25, v[4:5]
	v_mad_u64_u32 v[40:41], s[26:27], v35, s25, v[4:5]
	v_mad_u64_u32 v[42:43], s[26:27], v42, s25, v[4:5]
	v_mad_u64_u32 v[44:45], s[26:27], v44, s25, v[4:5]
	v_mad_u64_u32 v[66:67], s[26:27], v66, s25, v[4:5]
	v_mad_u64_u32 v[68:69], s[26:27], v68, s25, v[4:5]
	v_mad_u64_u32 v[70:71], s[26:27], v70, s25, v[4:5]
	v_mad_u64_u32 v[72:73], s[26:27], v72, s25, v[4:5]
	v_mad_u64_u32 v[74:75], s[26:27], v74, s25, v[4:5]
	v_mad_u64_u32 v[76:77], s[26:27], v76, s25, v[4:5]
	v_mad_u64_u32 v[78:79], s[26:27], v78, s25, v[4:5]
	v_mad_u64_u32 v[80:81], s[26:27], v80, s25, v[4:5]
	v_mad_u64_u32 v[82:83], s[26:27], v82, s25, v[4:5]
	v_mad_u64_u32 v[84:85], s[26:27], v84, s25, v[4:5]
	s_waitcnt vmcnt(15)
	ds_write_b32 v34, v33
	s_waitcnt vmcnt(14)
	ds_write_b32 v36, v65
	s_waitcnt vmcnt(13)
	ds_write_b32 v38, v86
	s_waitcnt vmcnt(12)
	ds_write_b32 v40, v87
	s_waitcnt vmcnt(4)
	ds_write_b32 v42, v95
	ds_write_b32 v44, v88
	ds_write_b32 v66, v94
	ds_write_b32 v68, v89
	s_waitcnt vmcnt(0)
	ds_write_b32 v70, v98
	ds_write_b32 v72, v90
	ds_write_b32 v74, v97
	ds_write_b32 v76, v91
	ds_write_b32 v78, v96
	ds_write_b32 v80, v92
	ds_write_b32 v82, v6
	ds_write_b32 v84, v93
	s_cbranch_scc1 .LBB0_108
	s_waitcnt lgkmcnt(0)
	ds_read2_b32 v[28:29], v48 offset1:33
	s_waitcnt lgkmcnt(0)
	v_cvt_pk_bf16_f32 v34, v28, v29
	ds_read2_b32 v[28:29], v48 offset0:66 offset1:99
	s_waitcnt lgkmcnt(0)
	v_cvt_pk_bf16_f32 v35, v28, v29
	ds_read2_b32 v[28:29], v48 offset0:132 offset1:165
	v_lshlrev_b32_e32 v6, 1, v32
	v_or_b32_e32 v3, v31, v47
	s_waitcnt lgkmcnt(0)
	v_cvt_pk_bf16_f32 v36, v28, v29
	ds_read2_b32 v[28:29], v48 offset0:198 offset1:231
	v_lshl_add_u64 v[38:39], v[16:17], 0, v[6:7]
	v_lshlrev_b32_e32 v6, 10, v3
	s_waitcnt lgkmcnt(0)
	v_cvt_pk_bf16_f32 v37, v28, v29
	ds_read2_b32 v[28:29], v48 offset0:8 offset1:41
	v_lshl_add_u64 v[32:33], v[38:39], 0, v[6:7]
	global_store_dwordx4 v[32:33], v[34:37], off
	s_waitcnt lgkmcnt(0)
	v_cvt_pk_bf16_f32 v32, v28, v29
	ds_read2_b32 v[28:29], v48 offset0:74 offset1:107
	s_waitcnt lgkmcnt(0)
	v_cvt_pk_bf16_f32 v33, v28, v29
	ds_read2_b32 v[28:29], v48 offset0:140 offset1:173
	v_or_b32_e32 v3, v31, v49
	s_waitcnt lgkmcnt(0)
	v_cvt_pk_bf16_f32 v34, v28, v29
	ds_read2_b32 v[28:29], v48 offset0:206 offset1:239
	v_lshlrev_b32_e32 v6, 10, v3
	s_waitcnt lgkmcnt(0)
	v_cvt_pk_bf16_f32 v35, v28, v29
	ds_read2_b32 v[28:29], v48 offset0:16 offset1:49
	v_lshl_add_u64 v[36:37], v[38:39], 0, v[6:7]
	global_store_dwordx4 v[36:37], v[32:35], off
	v_or_b32_e32 v3, v31, v50
	v_lshlrev_b32_e32 v6, 10, v3
	s_waitcnt lgkmcnt(0)
	v_cvt_pk_bf16_f32 v32, v28, v29
	ds_read2_b32 v[28:29], v48 offset0:82 offset1:115
	s_waitcnt lgkmcnt(0)
	v_cvt_pk_bf16_f32 v33, v28, v29
	ds_read2_b32 v[28:29], v48 offset0:148 offset1:181
	s_waitcnt lgkmcnt(0)
	v_cvt_pk_bf16_f32 v34, v28, v29
	ds_read2_b32 v[28:29], v48 offset0:214 offset1:247
	s_waitcnt lgkmcnt(0)
	v_cvt_pk_bf16_f32 v35, v28, v29
	ds_read2_b32 v[28:29], v48 offset0:24 offset1:57
	v_lshl_add_u64 v[36:37], v[38:39], 0, v[6:7]
	global_store_dwordx4 v[36:37], v[32:35], off
	s_waitcnt lgkmcnt(0)
	v_cvt_pk_bf16_f32 v28, v28, v29
	ds_read2_b32 v[32:33], v48 offset0:90 offset1:123
	s_waitcnt lgkmcnt(0)
	v_cvt_pk_bf16_f32 v29, v32, v33
	ds_read2_b32 v[32:33], v48 offset0:156 offset1:189
	v_or_b32_e32 v3, v31, v51
	s_waitcnt lgkmcnt(0)
	v_cvt_pk_bf16_f32 v30, v32, v33
	ds_read2_b32 v[32:33], v48 offset0:222 offset1:255
	v_lshlrev_b32_e32 v6, 10, v3
	s_waitcnt lgkmcnt(0)
	v_cvt_pk_bf16_f32 v31, v32, v33
	v_lshl_add_u64 v[32:33], v[38:39], 0, v[6:7]
	global_store_dwordx4 v[32:33], v[28:31], off
	s_waitcnt lgkmcnt(0)

.LBB0_113:
	s_lshl_b32 s22, s19, 1
	s_lshl_b32 s21, s18, 1
	v_or_b32_e32 v6, s22, v30
	s_add_i32 s27, s22, 4
	s_add_i32 s26, s21, 4
	s_add_i32 s39, s21, 8
	s_add_i32 s40, s22, 8
	v_lshlrev_b64 v[70:71], 12, v[6:7]
	v_or_b32_e32 v6, s27, v30
	v_mov_b32_e32 v35, v7
	v_mov_b32_e32 v37, v7
	v_mov_b32_e32 v39, v7
	v_or_b32_e32 v34, s21, v3
	s_add_i32 s41, s21, 12
	s_add_i32 s42, s22, 12
	s_add_i32 s43, s21, 16
	s_add_i32 s45, s21, 20
	s_add_i32 s47, s21, 24
	s_add_i32 s49, s21, 28
	v_or_b32_e32 v36, s26, v3
	v_or_b32_e32 v38, s39, v3
	v_lshlrev_b64 v[72:73], 12, v[6:7]
	v_or_b32_e32 v6, s40, v30
	v_mov_b32_e32 v41, v7
	v_mov_b32_e32 v43, v7
	v_mov_b32_e32 v45, v7
	v_mov_b32_e32 v67, v7
	v_mov_b32_e32 v69, v7
	s_add_i32 s44, s22, 16
	v_lshlrev_b64 v[34:35], 12, v[34:35]
	v_or_b32_e32 v40, s41, v3
	v_or_b32_e32 v42, s43, v3
	v_or_b32_e32 v44, s45, v3
	v_or_b32_e32 v66, s47, v3
	v_or_b32_e32 v68, s49, v3
	v_lshl_add_u64 v[70:71], v[28:29], 0, v[70:71]
	v_lshlrev_b64 v[36:37], 12, v[36:37]
	v_lshlrev_b64 v[38:39], 12, v[38:39]
	v_lshlrev_b64 v[74:75], 12, v[6:7]
	v_or_b32_e32 v6, s42, v30
	s_add_i32 s46, s22, 20
	v_lshl_add_u64 v[34:35], v[28:29], 0, v[34:35]
	v_lshlrev_b64 v[40:41], 12, v[40:41]
	v_lshlrev_b64 v[42:43], 12, v[42:43]
	v_lshlrev_b64 v[44:45], 12, v[44:45]
	v_lshlrev_b64 v[66:67], 12, v[66:67]
	v_lshlrev_b64 v[68:69], 12, v[68:69]
	v_lshl_add_u64 v[72:73], v[28:29], 0, v[72:73]
	v_lshl_add_u64 v[36:37], v[28:29], 0, v[36:37]
	v_lshl_add_u64 v[38:39], v[28:29], 0, v[38:39]
	global_load_dword v33, v[70:71], off nt
	global_load_dword v65, v[34:35], off nt
	v_lshlrev_b64 v[70:71], 12, v[6:7]
	v_or_b32_e32 v6, s44, v30
	s_add_i32 s48, s22, 24
	v_lshl_add_u64 v[40:41], v[28:29], 0, v[40:41]
	v_lshl_add_u64 v[42:43], v[28:29], 0, v[42:43]
	v_lshl_add_u64 v[44:45], v[28:29], 0, v[44:45]
	v_lshl_add_u64 v[66:67], v[28:29], 0, v[66:67]
	v_lshl_add_u64 v[68:69], v[28:29], 0, v[68:69]
	global_load_dword v86, v[72:73], off nt
	global_load_dword v87, v[36:37], off nt
	global_load_dword v88, v[38:39], off nt
	global_load_dword v89, v[40:41], off nt
	global_load_dword v90, v[42:43], off nt
	global_load_dword v91, v[44:45], off nt
	global_load_dword v92, v[66:67], off nt
	global_load_dword v93, v[68:69], off nt
	v_lshl_add_u64 v[36:37], v[28:29], 0, v[70:71]
	v_lshlrev_b64 v[38:39], 12, v[6:7]
	v_or_b32_e32 v6, s46, v30
	s_add_i32 s50, s22, 28
	v_lshl_add_u64 v[34:35], v[28:29], 0, v[74:75]
	global_load_dword v94, v[36:37], off nt
	global_load_dword v95, v[34:35], off nt
	v_lshlrev_b64 v[36:37], 12, v[6:7]
	v_or_b32_e32 v6, s48, v30
	v_lshl_add_u64 v[34:35], v[28:29], 0, v[38:39]
	v_lshlrev_b64 v[38:39], 12, v[6:7]
	v_or_b32_e32 v6, s50, v30
	v_lshlrev_b64 v[40:41], 12, v[6:7]
	v_lshl_add_u64 v[40:41], v[28:29], 0, v[40:41]
	v_lshl_add_u64 v[36:37], v[28:29], 0, v[36:37]
	v_lshl_add_u64 v[38:39], v[28:29], 0, v[38:39]
	global_load_dword v6, v[40:41], off nt
	global_load_dword v96, v[38:39], off nt
	global_load_dword v97, v[36:37], off nt
	global_load_dword v98, v[34:35], off nt
	v_or_b32_e32 v36, s21, v1
	v_or_b32_e32 v34, s22, v2
	s_add_i32 s19, s19, 16
	s_add_i32 s18, s18, 16
	s_add_i32 s20, s20, -16
	v_mad_u64_u32 v[34:35], s[22:23], v34, s25, v[4:5]
	v_mad_u64_u32 v[36:37], s[22:23], v36, s25, v[4:5]
	v_or_b32_e32 v35, s26, v1
	v_or_b32_e32 v37, s27, v2
	v_or_b32_e32 v44, s39, v1
	v_or_b32_e32 v42, s40, v2
	v_or_b32_e32 v68, s41, v1
	v_or_b32_e32 v66, s42, v2
	v_or_b32_e32 v72, s43, v1
	v_or_b32_e32 v70, s44, v2
	v_or_b32_e32 v76, s45, v1
	v_or_b32_e32 v74, s46, v2
	v_or_b32_e32 v80, s47, v1
	v_or_b32_e32 v78, s48, v2
	v_or_b32_e32 v84, s49, v1
	v_or_b32_e32 v82, s50, v2
	s_cmp_lg_u32 s20, 0
	v_mad_u64_u32 v[38:39], s[22:23], v37, s25, v[4:5]
	v_mad_u64_u32 v[40:41], s[22:23], v35, s25, v[4:5]
	v_mad_u64_u32 v[42:43], s[22:23], v42, s25, v[4:5]
	v_mad_u64_u32 v[44:45], s[22:23], v44, s25, v[4:5]
	v_mad_u64_u32 v[66:67], s[22:23], v66, s25, v[4:5]
	v_mad_u64_u32 v[68:69], s[22:23], v68, s25, v[4:5]
	v_mad_u64_u32 v[70:71], s[22:23], v70, s25, v[4:5]
	v_mad_u64_u32 v[72:73], s[22:23], v72, s25, v[4:5]
	v_mad_u64_u32 v[74:75], s[22:23], v74, s25, v[4:5]
	v_mad_u64_u32 v[76:77], s[22:23], v76, s25, v[4:5]
	v_mad_u64_u32 v[78:79], s[22:23], v78, s25, v[4:5]
	v_mad_u64_u32 v[80:81], s[22:23], v80, s25, v[4:5]
	v_mad_u64_u32 v[82:83], s[22:23], v82, s25, v[4:5]
	v_mad_u64_u32 v[84:85], s[22:23], v84, s25, v[4:5]
	s_waitcnt vmcnt(15)
	ds_write_b32 v34, v33
	s_waitcnt vmcnt(14)
	ds_write_b32 v36, v65
	s_waitcnt vmcnt(13)
	ds_write_b32 v38, v86
	s_waitcnt vmcnt(12)
	ds_write_b32 v40, v87
	s_waitcnt vmcnt(4)
	ds_write_b32 v42, v95
	ds_write_b32 v44, v88
	ds_write_b32 v66, v94
	ds_write_b32 v68, v89
	s_waitcnt vmcnt(0)
	ds_write_b32 v70, v98
	ds_write_b32 v72, v90
	ds_write_b32 v74, v97
	ds_write_b32 v76, v91
	ds_write_b32 v78, v96
	ds_write_b32 v80, v92
	ds_write_b32 v82, v6
	ds_write_b32 v84, v93
	s_cbranch_scc1 .LBB0_113
	s_waitcnt lgkmcnt(0)
	ds_read2_b32 v[28:29], v48 offset1:33
	s_waitcnt lgkmcnt(0)
	v_cvt_pk_bf16_f32 v34, v28, v29
	ds_read2_b32 v[28:29], v48 offset0:66 offset1:99
	s_waitcnt lgkmcnt(0)
	v_cvt_pk_bf16_f32 v35, v28, v29
	ds_read2_b32 v[28:29], v48 offset0:132 offset1:165
	v_lshlrev_b32_e32 v6, 1, v32
	v_or_b32_e32 v3, v31, v47
	s_waitcnt lgkmcnt(0)
	v_cvt_pk_bf16_f32 v36, v28, v29
	ds_read2_b32 v[28:29], v48 offset0:198 offset1:231
	v_lshl_add_u64 v[38:39], v[18:19], 0, v[6:7]
	v_lshlrev_b32_e32 v6, 10, v3
	s_waitcnt lgkmcnt(0)
	v_cvt_pk_bf16_f32 v37, v28, v29
	ds_read2_b32 v[28:29], v48 offset0:8 offset1:41
	v_lshl_add_u64 v[32:33], v[38:39], 0, v[6:7]
	global_store_dwordx4 v[32:33], v[34:37], off
	s_waitcnt lgkmcnt(0)
	v_cvt_pk_bf16_f32 v32, v28, v29
	ds_read2_b32 v[28:29], v48 offset0:74 offset1:107
	s_waitcnt lgkmcnt(0)
	v_cvt_pk_bf16_f32 v33, v28, v29
	ds_read2_b32 v[28:29], v48 offset0:140 offset1:173
	v_or_b32_e32 v3, v31, v49
	s_waitcnt lgkmcnt(0)
	v_cvt_pk_bf16_f32 v34, v28, v29
	ds_read2_b32 v[28:29], v48 offset0:206 offset1:239
	v_lshlrev_b32_e32 v6, 10, v3
	s_waitcnt lgkmcnt(0)
	v_cvt_pk_bf16_f32 v35, v28, v29
	ds_read2_b32 v[28:29], v48 offset0:16 offset1:49
	v_lshl_add_u64 v[36:37], v[38:39], 0, v[6:7]
	global_store_dwordx4 v[36:37], v[32:35], off
	v_or_b32_e32 v3, v31, v50
	v_lshlrev_b32_e32 v6, 10, v3
	s_waitcnt lgkmcnt(0)
	v_cvt_pk_bf16_f32 v32, v28, v29
	ds_read2_b32 v[28:29], v48 offset0:82 offset1:115
	s_waitcnt lgkmcnt(0)
	v_cvt_pk_bf16_f32 v33, v28, v29
	ds_read2_b32 v[28:29], v48 offset0:148 offset1:181
	s_waitcnt lgkmcnt(0)
	v_cvt_pk_bf16_f32 v34, v28, v29
	ds_read2_b32 v[28:29], v48 offset0:214 offset1:247
	s_waitcnt lgkmcnt(0)
	v_cvt_pk_bf16_f32 v35, v28, v29
	ds_read2_b32 v[28:29], v48 offset0:24 offset1:57
	v_lshl_add_u64 v[36:37], v[38:39], 0, v[6:7]
	global_store_dwordx4 v[36:37], v[32:35], off
	s_waitcnt lgkmcnt(0)
	v_cvt_pk_bf16_f32 v28, v28, v29
	ds_read2_b32 v[32:33], v48 offset0:90 offset1:123
	s_waitcnt lgkmcnt(0)
	v_cvt_pk_bf16_f32 v29, v32, v33
	ds_read2_b32 v[32:33], v48 offset0:156 offset1:189
	v_or_b32_e32 v3, v31, v51
	s_waitcnt lgkmcnt(0)
	v_cvt_pk_bf16_f32 v30, v32, v33
	ds_read2_b32 v[32:33], v48 offset0:222 offset1:255
	v_lshlrev_b32_e32 v6, 10, v3
	s_waitcnt lgkmcnt(0)
	v_cvt_pk_bf16_f32 v31, v32, v33
	v_lshl_add_u64 v[32:33], v[38:39], 0, v[6:7]
	global_store_dwordx4 v[32:33], v[28:31], off
	s_waitcnt lgkmcnt(0)

.LBB0_118:
	s_lshl_b32 s20, s18, 1
	s_lshl_b32 s19, s17, 1
	v_or_b32_e32 v6, s20, v30
	s_add_i32 s23, s20, 4
	s_add_i32 s22, s19, 4
	s_add_i32 s26, s19, 8
	s_add_i32 s27, s20, 8
	v_lshlrev_b64 v[70:71], 12, v[6:7]
	v_or_b32_e32 v6, s23, v30
	v_mov_b32_e32 v35, v7
	v_mov_b32_e32 v37, v7
	v_mov_b32_e32 v39, v7
	v_or_b32_e32 v34, s19, v3
	s_add_i32 s39, s19, 12
	s_add_i32 s40, s20, 12
	s_add_i32 s41, s19, 16
	s_add_i32 s43, s19, 20
	s_add_i32 s45, s19, 24
	s_add_i32 s47, s19, 28
	v_or_b32_e32 v36, s22, v3
	v_or_b32_e32 v38, s26, v3
	v_lshlrev_b64 v[72:73], 12, v[6:7]
	v_or_b32_e32 v6, s27, v30
	v_mov_b32_e32 v41, v7
	v_mov_b32_e32 v43, v7
	v_mov_b32_e32 v45, v7
	v_mov_b32_e32 v67, v7
	v_mov_b32_e32 v69, v7
	s_add_i32 s42, s20, 16
	v_lshlrev_b64 v[34:35], 12, v[34:35]
	v_or_b32_e32 v40, s39, v3
	v_or_b32_e32 v42, s41, v3
	v_or_b32_e32 v44, s43, v3
	v_or_b32_e32 v66, s45, v3
	v_or_b32_e32 v68, s47, v3
	v_lshl_add_u64 v[70:71], v[28:29], 0, v[70:71]
	v_lshlrev_b64 v[36:37], 12, v[36:37]
	v_lshlrev_b64 v[38:39], 12, v[38:39]
	v_lshlrev_b64 v[74:75], 12, v[6:7]
	v_or_b32_e32 v6, s40, v30
	s_add_i32 s44, s20, 20
	v_lshl_add_u64 v[34:35], v[28:29], 0, v[34:35]
	v_lshlrev_b64 v[40:41], 12, v[40:41]
	v_lshlrev_b64 v[42:43], 12, v[42:43]
	v_lshlrev_b64 v[44:45], 12, v[44:45]
	v_lshlrev_b64 v[66:67], 12, v[66:67]
	v_lshlrev_b64 v[68:69], 12, v[68:69]
	v_lshl_add_u64 v[72:73], v[28:29], 0, v[72:73]
	v_lshl_add_u64 v[36:37], v[28:29], 0, v[36:37]
	v_lshl_add_u64 v[38:39], v[28:29], 0, v[38:39]
	global_load_dword v33, v[70:71], off nt
	global_load_dword v65, v[34:35], off nt
	v_lshlrev_b64 v[70:71], 12, v[6:7]
	v_or_b32_e32 v6, s42, v30
	s_add_i32 s46, s20, 24
	v_lshl_add_u64 v[40:41], v[28:29], 0, v[40:41]
	v_lshl_add_u64 v[42:43], v[28:29], 0, v[42:43]
	v_lshl_add_u64 v[44:45], v[28:29], 0, v[44:45]
	v_lshl_add_u64 v[66:67], v[28:29], 0, v[66:67]
	v_lshl_add_u64 v[68:69], v[28:29], 0, v[68:69]
	global_load_dword v86, v[72:73], off nt
	global_load_dword v87, v[36:37], off nt
	global_load_dword v88, v[38:39], off nt
	global_load_dword v89, v[40:41], off nt
	global_load_dword v90, v[42:43], off nt
	global_load_dword v91, v[44:45], off nt
	global_load_dword v92, v[66:67], off nt
	global_load_dword v93, v[68:69], off nt
	v_lshl_add_u64 v[36:37], v[28:29], 0, v[70:71]
	v_lshlrev_b64 v[38:39], 12, v[6:7]
	v_or_b32_e32 v6, s44, v30
	s_add_i32 s48, s20, 28
	v_lshl_add_u64 v[34:35], v[28:29], 0, v[74:75]
	global_load_dword v94, v[36:37], off nt
	global_load_dword v95, v[34:35], off nt
	v_lshlrev_b64 v[36:37], 12, v[6:7]
	v_or_b32_e32 v6, s46, v30
	v_lshl_add_u64 v[34:35], v[28:29], 0, v[38:39]
	v_lshlrev_b64 v[38:39], 12, v[6:7]
	v_or_b32_e32 v6, s48, v30
	v_lshlrev_b64 v[40:41], 12, v[6:7]
	v_lshl_add_u64 v[40:41], v[28:29], 0, v[40:41]
	v_lshl_add_u64 v[36:37], v[28:29], 0, v[36:37]
	v_lshl_add_u64 v[38:39], v[28:29], 0, v[38:39]
	global_load_dword v6, v[40:41], off nt
	global_load_dword v96, v[38:39], off nt
	global_load_dword v97, v[36:37], off nt
	global_load_dword v98, v[34:35], off nt
	v_or_b32_e32 v36, s19, v1
	v_or_b32_e32 v34, s20, v2
	s_add_i32 s18, s18, 16
	s_add_i32 s17, s17, 16
	s_add_i32 s16, s16, -16
	v_mad_u64_u32 v[34:35], s[20:21], v34, s25, v[4:5]
	v_mad_u64_u32 v[36:37], s[20:21], v36, s25, v[4:5]
	v_or_b32_e32 v35, s22, v1
	v_or_b32_e32 v37, s23, v2
	v_or_b32_e32 v44, s26, v1
	v_or_b32_e32 v42, s27, v2
	v_or_b32_e32 v68, s39, v1
	v_or_b32_e32 v66, s40, v2
	v_or_b32_e32 v72, s41, v1
	v_or_b32_e32 v70, s42, v2
	v_or_b32_e32 v76, s43, v1
	v_or_b32_e32 v74, s44, v2
	v_or_b32_e32 v80, s45, v1
	v_or_b32_e32 v78, s46, v2
	v_or_b32_e32 v84, s47, v1
	v_or_b32_e32 v82, s48, v2
	s_cmp_lg_u32 s16, 0
	v_mad_u64_u32 v[38:39], s[20:21], v37, s25, v[4:5]
	v_mad_u64_u32 v[40:41], s[20:21], v35, s25, v[4:5]
	v_mad_u64_u32 v[42:43], s[20:21], v42, s25, v[4:5]
	v_mad_u64_u32 v[44:45], s[20:21], v44, s25, v[4:5]
	v_mad_u64_u32 v[66:67], s[20:21], v66, s25, v[4:5]
	v_mad_u64_u32 v[68:69], s[20:21], v68, s25, v[4:5]
	v_mad_u64_u32 v[70:71], s[20:21], v70, s25, v[4:5]
	v_mad_u64_u32 v[72:73], s[20:21], v72, s25, v[4:5]
	v_mad_u64_u32 v[74:75], s[20:21], v74, s25, v[4:5]
	v_mad_u64_u32 v[76:77], s[20:21], v76, s25, v[4:5]
	v_mad_u64_u32 v[78:79], s[20:21], v78, s25, v[4:5]
	v_mad_u64_u32 v[80:81], s[20:21], v80, s25, v[4:5]
	v_mad_u64_u32 v[82:83], s[20:21], v82, s25, v[4:5]
	v_mad_u64_u32 v[84:85], s[20:21], v84, s25, v[4:5]
	s_waitcnt vmcnt(15)
	ds_write_b32 v34, v33
	s_waitcnt vmcnt(14)
	ds_write_b32 v36, v65
	s_waitcnt vmcnt(13)
	ds_write_b32 v38, v86
	s_waitcnt vmcnt(12)
	ds_write_b32 v40, v87
	s_waitcnt vmcnt(4)
	ds_write_b32 v42, v95
	ds_write_b32 v44, v88
	ds_write_b32 v66, v94
	ds_write_b32 v68, v89
	s_waitcnt vmcnt(0)
	ds_write_b32 v70, v98
	ds_write_b32 v72, v90
	ds_write_b32 v74, v97
	ds_write_b32 v76, v91
	ds_write_b32 v78, v96
	ds_write_b32 v80, v92
	ds_write_b32 v82, v6
	ds_write_b32 v84, v93
	s_cbranch_scc1 .LBB0_118
	s_waitcnt lgkmcnt(0)
	ds_read2_b32 v[28:29], v48 offset1:33
	s_waitcnt lgkmcnt(0)
	v_cvt_pk_bf16_f32 v34, v28, v29
	ds_read2_b32 v[28:29], v48 offset0:66 offset1:99
	s_waitcnt lgkmcnt(0)
	v_cvt_pk_bf16_f32 v35, v28, v29
	ds_read2_b32 v[28:29], v48 offset0:132 offset1:165
	v_lshlrev_b32_e32 v6, 1, v32
	v_or_b32_e32 v3, v31, v47
	s_waitcnt lgkmcnt(0)
	v_cvt_pk_bf16_f32 v36, v28, v29
	ds_read2_b32 v[28:29], v48 offset0:198 offset1:231
	v_lshl_add_u64 v[38:39], v[20:21], 0, v[6:7]
	v_lshlrev_b32_e32 v6, 9, v3
	s_waitcnt lgkmcnt(0)
	v_cvt_pk_bf16_f32 v37, v28, v29
	ds_read2_b32 v[28:29], v48 offset0:8 offset1:41
	v_lshl_add_u64 v[32:33], v[38:39], 0, v[6:7]
	global_store_dwordx4 v[32:33], v[34:37], off
	s_waitcnt lgkmcnt(0)
	v_cvt_pk_bf16_f32 v32, v28, v29
	ds_read2_b32 v[28:29], v48 offset0:74 offset1:107
	s_waitcnt lgkmcnt(0)
	v_cvt_pk_bf16_f32 v33, v28, v29
	ds_read2_b32 v[28:29], v48 offset0:140 offset1:173
	v_or_b32_e32 v3, v31, v49
	s_waitcnt lgkmcnt(0)
	v_cvt_pk_bf16_f32 v34, v28, v29
	ds_read2_b32 v[28:29], v48 offset0:206 offset1:239
	v_lshlrev_b32_e32 v6, 9, v3
	s_waitcnt lgkmcnt(0)
	v_cvt_pk_bf16_f32 v35, v28, v29
	ds_read2_b32 v[28:29], v48 offset0:16 offset1:49
	v_lshl_add_u64 v[36:37], v[38:39], 0, v[6:7]
	global_store_dwordx4 v[36:37], v[32:35], off
	v_or_b32_e32 v3, v31, v50
	v_lshlrev_b32_e32 v6, 9, v3
	s_waitcnt lgkmcnt(0)
	v_cvt_pk_bf16_f32 v32, v28, v29
	ds_read2_b32 v[28:29], v48 offset0:82 offset1:115
	s_waitcnt lgkmcnt(0)
	v_cvt_pk_bf16_f32 v33, v28, v29
	ds_read2_b32 v[28:29], v48 offset0:148 offset1:181
	s_waitcnt lgkmcnt(0)
	v_cvt_pk_bf16_f32 v34, v28, v29
	ds_read2_b32 v[28:29], v48 offset0:214 offset1:247
	s_waitcnt lgkmcnt(0)
	v_cvt_pk_bf16_f32 v35, v28, v29
	ds_read2_b32 v[28:29], v48 offset0:24 offset1:57
	v_lshl_add_u64 v[36:37], v[38:39], 0, v[6:7]
	global_store_dwordx4 v[36:37], v[32:35], off
	s_waitcnt lgkmcnt(0)
	v_cvt_pk_bf16_f32 v28, v28, v29
	ds_read2_b32 v[32:33], v48 offset0:90 offset1:123
	s_waitcnt lgkmcnt(0)
	v_cvt_pk_bf16_f32 v29, v32, v33
	ds_read2_b32 v[32:33], v48 offset0:156 offset1:189
	v_or_b32_e32 v3, v31, v51
	s_waitcnt lgkmcnt(0)
	v_cvt_pk_bf16_f32 v30, v32, v33
	ds_read2_b32 v[32:33], v48 offset0:222 offset1:255
	v_lshlrev_b32_e32 v6, 9, v3
	s_waitcnt lgkmcnt(0)
	v_cvt_pk_bf16_f32 v31, v32, v33
	v_lshl_add_u64 v[32:33], v[38:39], 0, v[6:7]
	global_store_dwordx4 v[32:33], v[28:31], off
	s_waitcnt lgkmcnt(0)

.LBB0_123:
	s_lshl_b32 s18, s16, 1
	s_lshl_b32 s17, s15, 1
	v_or_b32_e32 v6, s18, v30
	s_add_i32 s21, s18, 4
	s_add_i32 s20, s17, 4
	s_add_i32 s22, s17, 8
	s_add_i32 s23, s18, 8
	v_lshlrev_b64 v[70:71], 12, v[6:7]
	v_or_b32_e32 v6, s21, v30
	v_mov_b32_e32 v35, v7
	v_mov_b32_e32 v37, v7
	v_mov_b32_e32 v39, v7
	v_or_b32_e32 v34, s17, v3
	s_add_i32 s26, s17, 12
	s_add_i32 s27, s18, 12
	s_add_i32 s39, s17, 16
	s_add_i32 s41, s17, 20
	s_add_i32 s43, s17, 24
	s_add_i32 s45, s17, 28
	v_or_b32_e32 v36, s20, v3
	v_or_b32_e32 v38, s22, v3
	v_lshlrev_b64 v[72:73], 12, v[6:7]
	v_or_b32_e32 v6, s23, v30
	v_mov_b32_e32 v41, v7
	v_mov_b32_e32 v43, v7
	v_mov_b32_e32 v45, v7
	v_mov_b32_e32 v67, v7
	v_mov_b32_e32 v69, v7
	s_add_i32 s40, s18, 16
	v_lshlrev_b64 v[34:35], 12, v[34:35]
	v_or_b32_e32 v40, s26, v3
	v_or_b32_e32 v42, s39, v3
	v_or_b32_e32 v44, s41, v3
	v_or_b32_e32 v66, s43, v3
	v_or_b32_e32 v68, s45, v3
	v_lshl_add_u64 v[70:71], v[28:29], 0, v[70:71]
	v_lshlrev_b64 v[36:37], 12, v[36:37]
	v_lshlrev_b64 v[38:39], 12, v[38:39]
	v_lshlrev_b64 v[74:75], 12, v[6:7]
	v_or_b32_e32 v6, s27, v30
	s_add_i32 s42, s18, 20
	v_lshl_add_u64 v[34:35], v[28:29], 0, v[34:35]
	v_lshlrev_b64 v[40:41], 12, v[40:41]
	v_lshlrev_b64 v[42:43], 12, v[42:43]
	v_lshlrev_b64 v[44:45], 12, v[44:45]
	v_lshlrev_b64 v[66:67], 12, v[66:67]
	v_lshlrev_b64 v[68:69], 12, v[68:69]
	v_lshl_add_u64 v[72:73], v[28:29], 0, v[72:73]
	v_lshl_add_u64 v[36:37], v[28:29], 0, v[36:37]
	v_lshl_add_u64 v[38:39], v[28:29], 0, v[38:39]
	global_load_dword v33, v[70:71], off nt
	global_load_dword v65, v[34:35], off nt
	v_lshlrev_b64 v[70:71], 12, v[6:7]
	v_or_b32_e32 v6, s40, v30
	s_add_i32 s44, s18, 24
	v_lshl_add_u64 v[40:41], v[28:29], 0, v[40:41]
	v_lshl_add_u64 v[42:43], v[28:29], 0, v[42:43]
	v_lshl_add_u64 v[44:45], v[28:29], 0, v[44:45]
	v_lshl_add_u64 v[66:67], v[28:29], 0, v[66:67]
	v_lshl_add_u64 v[68:69], v[28:29], 0, v[68:69]
	global_load_dword v86, v[72:73], off nt
	global_load_dword v87, v[36:37], off nt
	global_load_dword v88, v[38:39], off nt
	global_load_dword v89, v[40:41], off nt
	global_load_dword v90, v[42:43], off nt
	global_load_dword v91, v[44:45], off nt
	global_load_dword v92, v[66:67], off nt
	global_load_dword v93, v[68:69], off nt
	v_lshl_add_u64 v[36:37], v[28:29], 0, v[70:71]
	v_lshlrev_b64 v[38:39], 12, v[6:7]
	v_or_b32_e32 v6, s42, v30
	s_add_i32 s46, s18, 28
	v_lshl_add_u64 v[34:35], v[28:29], 0, v[74:75]
	global_load_dword v94, v[36:37], off nt
	global_load_dword v95, v[34:35], off nt
	v_lshlrev_b64 v[36:37], 12, v[6:7]
	v_or_b32_e32 v6, s44, v30
	v_lshl_add_u64 v[34:35], v[28:29], 0, v[38:39]
	v_lshlrev_b64 v[38:39], 12, v[6:7]
	v_or_b32_e32 v6, s46, v30
	v_lshlrev_b64 v[40:41], 12, v[6:7]
	v_lshl_add_u64 v[40:41], v[28:29], 0, v[40:41]
	v_lshl_add_u64 v[36:37], v[28:29], 0, v[36:37]
	v_lshl_add_u64 v[38:39], v[28:29], 0, v[38:39]
	global_load_dword v6, v[40:41], off nt
	global_load_dword v96, v[38:39], off nt
	global_load_dword v97, v[36:37], off nt
	global_load_dword v98, v[34:35], off nt
	v_or_b32_e32 v36, s17, v1
	v_or_b32_e32 v34, s18, v2
	s_add_i32 s16, s16, 16
	s_add_i32 s15, s15, 16
	s_add_i32 s14, s14, -16
	v_mad_u64_u32 v[34:35], s[18:19], v34, s25, v[4:5]
	v_mad_u64_u32 v[36:37], s[18:19], v36, s25, v[4:5]
	v_or_b32_e32 v35, s20, v1
	v_or_b32_e32 v37, s21, v2
	v_or_b32_e32 v44, s22, v1
	v_or_b32_e32 v42, s23, v2
	v_or_b32_e32 v68, s26, v1
	v_or_b32_e32 v66, s27, v2
	v_or_b32_e32 v72, s39, v1
	v_or_b32_e32 v70, s40, v2
	v_or_b32_e32 v76, s41, v1
	v_or_b32_e32 v74, s42, v2
	v_or_b32_e32 v80, s43, v1
	v_or_b32_e32 v78, s44, v2
	v_or_b32_e32 v84, s45, v1
	v_or_b32_e32 v82, s46, v2
	s_cmp_lg_u32 s14, 0
	v_mad_u64_u32 v[38:39], s[18:19], v37, s25, v[4:5]
	v_mad_u64_u32 v[40:41], s[18:19], v35, s25, v[4:5]
	v_mad_u64_u32 v[42:43], s[18:19], v42, s25, v[4:5]
	v_mad_u64_u32 v[44:45], s[18:19], v44, s25, v[4:5]
	v_mad_u64_u32 v[66:67], s[18:19], v66, s25, v[4:5]
	v_mad_u64_u32 v[68:69], s[18:19], v68, s25, v[4:5]
	v_mad_u64_u32 v[70:71], s[18:19], v70, s25, v[4:5]
	v_mad_u64_u32 v[72:73], s[18:19], v72, s25, v[4:5]
	v_mad_u64_u32 v[74:75], s[18:19], v74, s25, v[4:5]
	v_mad_u64_u32 v[76:77], s[18:19], v76, s25, v[4:5]
	v_mad_u64_u32 v[78:79], s[18:19], v78, s25, v[4:5]
	v_mad_u64_u32 v[80:81], s[18:19], v80, s25, v[4:5]
	v_mad_u64_u32 v[82:83], s[18:19], v82, s25, v[4:5]
	v_mad_u64_u32 v[84:85], s[18:19], v84, s25, v[4:5]
	s_waitcnt vmcnt(15)
	ds_write_b32 v34, v33
	s_waitcnt vmcnt(14)
	ds_write_b32 v36, v65
	s_waitcnt vmcnt(13)
	ds_write_b32 v38, v86
	s_waitcnt vmcnt(12)
	ds_write_b32 v40, v87
	s_waitcnt vmcnt(4)
	ds_write_b32 v42, v95
	ds_write_b32 v44, v88
	ds_write_b32 v66, v94
	ds_write_b32 v68, v89
	s_waitcnt vmcnt(0)
	ds_write_b32 v70, v98
	ds_write_b32 v72, v90
	ds_write_b32 v74, v97
	ds_write_b32 v76, v91
	ds_write_b32 v78, v96
	ds_write_b32 v80, v92
	ds_write_b32 v82, v6
	ds_write_b32 v84, v93
	s_cbranch_scc1 .LBB0_123
	s_waitcnt lgkmcnt(0)
	ds_read2_b32 v[28:29], v48 offset1:33
	v_and_b32_e32 v3, 0x1e0, v32
	v_lshlrev_b32_e32 v6, 1, v31
	s_waitcnt lgkmcnt(0)
	v_cvt_pk_bf16_f32 v28, v28, v29
	ds_read2_b32 v[34:35], v48 offset0:66 offset1:99
	v_lshl_add_u64 v[32:33], v[22:23], 0, v[6:7]
	v_or_b32_e32 v6, v3, v47
	s_waitcnt lgkmcnt(0)
	v_cvt_pk_bf16_f32 v29, v34, v35
	ds_read2_b32 v[34:35], v48 offset0:132 offset1:165
	v_lshlrev_b32_e32 v6, 9, v6
	s_waitcnt lgkmcnt(0)
	v_cvt_pk_bf16_f32 v30, v34, v35
	ds_read2_b32 v[34:35], v48 offset0:198 offset1:231
	s_waitcnt lgkmcnt(0)
	v_cvt_pk_bf16_f32 v31, v34, v35
	v_lshl_add_u64 v[36:37], v[32:33], 0, v[6:7]
	ds_read2_b32 v[34:35], v48 offset0:8 offset1:41
	global_store_dwordx4 v[36:37], v[28:31], off
	v_or_b32_e32 v6, v3, v49
	v_lshlrev_b32_e32 v6, 9, v6
	s_waitcnt lgkmcnt(0)
	v_cvt_pk_bf16_f32 v28, v34, v35
	ds_read2_b32 v[30:31], v48 offset0:74 offset1:107
	s_waitcnt lgkmcnt(0)
	v_cvt_pk_bf16_f32 v29, v30, v31
	ds_read2_b32 v[30:31], v48 offset0:140 offset1:173
	s_waitcnt lgkmcnt(0)
	v_cvt_pk_bf16_f32 v30, v30, v31
	ds_read2_b32 v[34:35], v48 offset0:206 offset1:239
	s_waitcnt lgkmcnt(0)
	v_cvt_pk_bf16_f32 v31, v34, v35
	v_lshl_add_u64 v[36:37], v[32:33], 0, v[6:7]
	ds_read2_b32 v[34:35], v48 offset0:16 offset1:49
	global_store_dwordx4 v[36:37], v[28:31], off
	v_or_b32_e32 v6, v3, v50
	v_lshlrev_b32_e32 v6, 9, v6
	s_waitcnt lgkmcnt(0)
	v_cvt_pk_bf16_f32 v28, v34, v35
	ds_read2_b32 v[30:31], v48 offset0:82 offset1:115
	s_waitcnt lgkmcnt(0)
	v_cvt_pk_bf16_f32 v29, v30, v31
	ds_read2_b32 v[30:31], v48 offset0:148 offset1:181
	s_waitcnt lgkmcnt(0)
	v_cvt_pk_bf16_f32 v30, v30, v31
	ds_read2_b32 v[34:35], v48 offset0:214 offset1:247
	s_waitcnt lgkmcnt(0)
	v_cvt_pk_bf16_f32 v31, v34, v35
	v_lshl_add_u64 v[36:37], v[32:33], 0, v[6:7]
	v_or_b32_e32 v3, v3, v51
	ds_read2_b32 v[34:35], v48 offset0:24 offset1:57
	global_store_dwordx4 v[36:37], v[28:31], off
	v_lshlrev_b32_e32 v6, 9, v3
	v_lshl_add_u64 v[32:33], v[32:33], 0, v[6:7]
	s_waitcnt lgkmcnt(0)
	v_cvt_pk_bf16_f32 v28, v34, v35
	ds_read2_b32 v[30:31], v48 offset0:90 offset1:123
	s_waitcnt lgkmcnt(0)
	v_cvt_pk_bf16_f32 v29, v30, v31
	ds_read2_b32 v[30:31], v48 offset0:156 offset1:189
	s_waitcnt lgkmcnt(0)
	v_cvt_pk_bf16_f32 v30, v30, v31
	ds_read2_b32 v[34:35], v48 offset0:222 offset1:255
	s_waitcnt lgkmcnt(0)
	v_cvt_pk_bf16_f32 v31, v34, v35
	global_store_dwordx4 v[32:33], v[28:31], off
	s_waitcnt lgkmcnt(0)

.LBB0_128:
	s_lshl_b32 s15, s12, 1
	s_lshl_b32 s18, s13, 1
	v_or_b32_e32 v32, s18, v6
	s_add_i32 s19, s15, 4
	s_add_i32 s20, s18, 4
	s_add_i32 s21, s15, 8
	s_add_i32 s22, s18, 8
	s_add_i32 s23, s15, 12
	s_add_i32 s26, s18, 12
	s_add_i32 s27, s15, 16
	s_add_i32 s39, s18, 16
	s_add_i32 s40, s15, 20
	s_add_i32 s41, s18, 20
	s_add_i32 s42, s15, 24
	s_add_i32 s43, s18, 24
	s_add_i32 s44, s15, 28
	s_add_i32 s45, s18, 28
	v_or_b32_e32 v34, s15, v3
	v_mad_u64_u32 v[32:33], s[16:17], v32, s37, v[28:29]
	v_or_b32_e32 v38, s19, v3
	v_or_b32_e32 v36, s20, v6
	v_or_b32_e32 v42, s21, v3
	v_or_b32_e32 v40, s22, v6
	v_or_b32_e32 v65, s23, v3
	v_or_b32_e32 v44, s26, v6
	v_or_b32_e32 v70, s27, v3
	v_or_b32_e32 v68, s39, v6
	v_or_b32_e32 v74, s40, v3
	v_or_b32_e32 v72, s41, v6
	v_or_b32_e32 v78, s42, v3
	v_or_b32_e32 v76, s43, v6
	v_or_b32_e32 v82, s44, v3
	v_or_b32_e32 v80, s45, v6
	v_mad_u64_u32 v[34:35], s[16:17], v34, s37, v[28:29]
	v_mad_u64_u32 v[36:37], s[16:17], v36, s37, v[28:29]
	v_mad_u64_u32 v[38:39], s[16:17], v38, s37, v[28:29]
	v_mad_u64_u32 v[40:41], s[16:17], v40, s37, v[28:29]
	v_mad_u64_u32 v[42:43], s[16:17], v42, s37, v[28:29]
	v_mad_u64_u32 v[44:45], s[16:17], v44, s37, v[28:29]
	v_mad_u64_u32 v[66:67], s[16:17], v65, s37, v[28:29]
	v_mad_u64_u32 v[68:69], s[16:17], v68, s37, v[28:29]
	v_mad_u64_u32 v[70:71], s[16:17], v70, s37, v[28:29]
	v_mad_u64_u32 v[72:73], s[16:17], v72, s37, v[28:29]
	v_mad_u64_u32 v[74:75], s[16:17], v74, s37, v[28:29]
	v_mad_u64_u32 v[76:77], s[16:17], v76, s37, v[28:29]
	v_mad_u64_u32 v[78:79], s[16:17], v78, s37, v[28:29]
	v_mad_u64_u32 v[80:81], s[16:17], v80, s37, v[28:29]
	v_mad_u64_u32 v[82:83], s[16:17], v82, s37, v[28:29]
	global_load_dword v65, v[32:33], off nt
	global_load_dword v84, v[34:35], off nt
	global_load_dword v85, v[36:37], off nt
	global_load_dword v86, v[38:39], off nt
	global_load_dword v87, v[40:41], off nt
	global_load_dword v88, v[42:43], off nt
	global_load_dword v89, v[44:45], off nt
	global_load_dword v90, v[66:67], off nt
	global_load_dword v91, v[68:69], off nt
	global_load_dword v92, v[70:71], off nt
	global_load_dword v93, v[72:73], off nt
	global_load_dword v94, v[74:75], off nt
	global_load_dword v95, v[76:77], off nt
	global_load_dword v96, v[78:79], off nt
	global_load_dword v97, v[80:81], off nt
	global_load_dword v98, v[82:83], off nt
	v_or_b32_e32 v34, s15, v1
	v_or_b32_e32 v32, s18, v2
	s_add_i32 s13, s13, 16
	s_add_i32 s12, s12, 16
	s_add_i32 s14, s14, -16
	v_mad_u64_u32 v[32:33], s[16:17], v32, s25, v[4:5]
	v_mad_u64_u32 v[34:35], s[16:17], v34, s25, v[4:5]
	v_or_b32_e32 v33, s19, v1
	v_or_b32_e32 v35, s20, v2
	v_or_b32_e32 v42, s21, v1
	v_or_b32_e32 v40, s22, v2
	v_or_b32_e32 v66, s23, v1
	v_or_b32_e32 v44, s26, v2
	v_or_b32_e32 v70, s27, v1
	v_or_b32_e32 v68, s39, v2
	v_or_b32_e32 v74, s40, v1
	v_or_b32_e32 v72, s41, v2
	v_or_b32_e32 v78, s42, v1
	v_or_b32_e32 v76, s43, v2
	v_or_b32_e32 v82, s44, v1
	v_or_b32_e32 v80, s45, v2
	s_cmp_lg_u32 s14, 0
	v_mad_u64_u32 v[36:37], s[16:17], v35, s25, v[4:5]
	v_mad_u64_u32 v[38:39], s[16:17], v33, s25, v[4:5]
	v_mad_u64_u32 v[40:41], s[16:17], v40, s25, v[4:5]
	v_mad_u64_u32 v[42:43], s[16:17], v42, s25, v[4:5]
	v_mad_u64_u32 v[44:45], s[16:17], v44, s25, v[4:5]
	v_mad_u64_u32 v[66:67], s[16:17], v66, s25, v[4:5]
	v_mad_u64_u32 v[68:69], s[16:17], v68, s25, v[4:5]
	v_mad_u64_u32 v[70:71], s[16:17], v70, s25, v[4:5]
	v_mad_u64_u32 v[72:73], s[16:17], v72, s25, v[4:5]
	v_mad_u64_u32 v[74:75], s[16:17], v74, s25, v[4:5]
	v_mad_u64_u32 v[76:77], s[16:17], v76, s25, v[4:5]
	v_mad_u64_u32 v[78:79], s[16:17], v78, s25, v[4:5]
	v_mad_u64_u32 v[80:81], s[16:17], v80, s25, v[4:5]
	v_mad_u64_u32 v[82:83], s[16:17], v82, s25, v[4:5]
	s_waitcnt vmcnt(15)
	ds_write_b32 v32, v65
	s_waitcnt vmcnt(14)
	ds_write_b32 v34, v84
	s_waitcnt vmcnt(13)
	ds_write_b32 v36, v85
	s_waitcnt vmcnt(12)
	ds_write_b32 v38, v86
	s_waitcnt vmcnt(11)
	ds_write_b32 v40, v87
	s_waitcnt vmcnt(10)
	ds_write_b32 v42, v88
	s_waitcnt vmcnt(9)
	ds_write_b32 v44, v89
	s_waitcnt vmcnt(8)
	ds_write_b32 v66, v90
	s_waitcnt vmcnt(7)
	ds_write_b32 v68, v91
	s_waitcnt vmcnt(6)
	ds_write_b32 v70, v92
	s_waitcnt vmcnt(5)
	ds_write_b32 v72, v93
	s_waitcnt vmcnt(4)
	ds_write_b32 v74, v94
	s_waitcnt vmcnt(3)
	ds_write_b32 v76, v95
	s_waitcnt vmcnt(2)
	ds_write_b32 v78, v96
	s_waitcnt vmcnt(1)
	ds_write_b32 v80, v97
	s_waitcnt vmcnt(0)
	ds_write_b32 v82, v98
	s_cbranch_scc1 .LBB0_128
	s_waitcnt lgkmcnt(0)
	ds_read2_b32 v[28:29], v48 offset1:33
	s_waitcnt lgkmcnt(0)
	v_cvt_pk_bf16_f32 v32, v28, v29
	ds_read2_b32 v[28:29], v48 offset0:66 offset1:99
	v_or_b32_e32 v3, v30, v47
	s_waitcnt lgkmcnt(0)
	v_cvt_pk_bf16_f32 v33, v28, v29
	ds_read2_b32 v[28:29], v48 offset0:132 offset1:165
	v_lshlrev_b32_e32 v6, 1, v31
	v_mul_u32_u24_e32 v3, 0x180, v3
	s_waitcnt lgkmcnt(0)
	v_cvt_pk_bf16_f32 v34, v28, v29
	ds_read2_b32 v[28:29], v48 offset0:198 offset1:231
	v_lshl_add_u64 v[36:37], v[24:25], 0, v[6:7]
	v_lshlrev_b32_e32 v6, 1, v3
	s_waitcnt lgkmcnt(0)
	v_cvt_pk_bf16_f32 v35, v28, v29
	ds_read2_b32 v[28:29], v48 offset0:8 offset1:41
	v_lshl_add_u64 v[38:39], v[36:37], 0, v[6:7]
	global_store_dwordx4 v[38:39], v[32:35], off
	v_or_b32_e32 v3, v30, v49
	v_mul_u32_u24_e32 v3, 0x180, v3
	s_waitcnt lgkmcnt(0)
	v_cvt_pk_bf16_f32 v32, v28, v29
	ds_read2_b32 v[28:29], v48 offset0:74 offset1:107
	s_waitcnt lgkmcnt(0)
	v_cvt_pk_bf16_f32 v33, v28, v29
	ds_read2_b32 v[28:29], v48 offset0:140 offset1:173
	s_waitcnt lgkmcnt(0)
	v_cvt_pk_bf16_f32 v34, v28, v29
	ds_read2_b32 v[28:29], v48 offset0:206 offset1:239
	v_lshlrev_b32_e32 v6, 1, v3
	s_waitcnt lgkmcnt(0)
	v_cvt_pk_bf16_f32 v35, v28, v29
	ds_read2_b32 v[28:29], v48 offset0:16 offset1:49
	v_lshl_add_u64 v[38:39], v[36:37], 0, v[6:7]
	global_store_dwordx4 v[38:39], v[32:35], off
	v_or_b32_e32 v3, v30, v50
	v_mul_u32_u24_e32 v3, 0x180, v3
	s_waitcnt lgkmcnt(0)
	v_cvt_pk_bf16_f32 v32, v28, v29
	ds_read2_b32 v[28:29], v48 offset0:82 offset1:115
	s_waitcnt lgkmcnt(0)
	v_cvt_pk_bf16_f32 v33, v28, v29
	ds_read2_b32 v[28:29], v48 offset0:148 offset1:181
	s_waitcnt lgkmcnt(0)
	v_cvt_pk_bf16_f32 v34, v28, v29
	ds_read2_b32 v[28:29], v48 offset0:214 offset1:247
	v_lshlrev_b32_e32 v6, 1, v3
	s_waitcnt lgkmcnt(0)
	v_cvt_pk_bf16_f32 v35, v28, v29
	ds_read2_b32 v[28:29], v48 offset0:24 offset1:57
	v_lshl_add_u64 v[38:39], v[36:37], 0, v[6:7]
	global_store_dwordx4 v[38:39], v[32:35], off
	v_or_b32_e32 v3, v30, v51
	v_mul_u32_u24_e32 v3, 0x180, v3
	s_waitcnt lgkmcnt(0)
	v_cvt_pk_bf16_f32 v32, v28, v29
	ds_read2_b32 v[28:29], v48 offset0:90 offset1:123
	s_waitcnt lgkmcnt(0)
	v_cvt_pk_bf16_f32 v33, v28, v29
	ds_read2_b32 v[28:29], v48 offset0:156 offset1:189
	s_waitcnt lgkmcnt(0)
	v_cvt_pk_bf16_f32 v34, v28, v29
	ds_read2_b32 v[28:29], v48 offset0:222 offset1:255
	v_lshlrev_b32_e32 v6, 1, v3
	s_waitcnt lgkmcnt(0)
	v_cvt_pk_bf16_f32 v35, v28, v29
	v_lshl_add_u64 v[28:29], v[36:37], 0, v[6:7]
	global_store_dwordx4 v[28:29], v[32:35], off
	s_waitcnt lgkmcnt(0)

.LBB0_154:
	v_mov_b32_e32 v29, 0
	v_mov_b32_e32 v65, 0
	s_and_saveexec_b64 s[12:13], vcc
	s_cbranch_execz .LBB0_156
	v_lshl_add_u64 v[66:67], v[44:45], 0, s[10:11]
	global_load_dword v65, v[66:67], off nt
.LBB0_156:
	s_or_b64 exec, exec, s[12:13]
	s_waitcnt vmcnt(0)
	ds_write_b32 v6, v65
	s_and_saveexec_b64 s[12:13], vcc
	s_cbranch_execz .LBB0_158
	v_lshl_add_u64 v[66:67], v[42:43], 0, s[10:11]
	global_load_dword v29, v[66:67], off nt
.LBB0_158:
	s_or_b64 exec, exec, s[12:13]
	s_waitcnt vmcnt(0)
	ds_write_b32 v6, v29 offset:264
	v_mov_b32_e32 v29, 0
	v_mov_b32_e32 v65, 0
	s_and_saveexec_b64 s[12:13], vcc
	s_cbranch_execz .LBB0_160
	v_lshl_add_u64 v[66:67], v[40:41], 0, s[10:11]
	global_load_dword v65, v[66:67], off nt
.LBB0_160:
	s_or_b64 exec, exec, s[12:13]
	s_waitcnt vmcnt(0)
	ds_write_b32 v6, v65 offset:528
	s_and_saveexec_b64 s[12:13], vcc
	s_cbranch_execz .LBB0_162
	v_lshl_add_u64 v[66:67], v[38:39], 0, s[10:11]
	global_load_dword v29, v[66:67], off nt
.LBB0_162:
	s_or_b64 exec, exec, s[12:13]
	s_waitcnt vmcnt(0)
	ds_write_b32 v6, v29 offset:792
	v_mov_b32_e32 v29, 0
	v_mov_b32_e32 v65, 0
	s_and_saveexec_b64 s[12:13], vcc
	s_cbranch_execz .LBB0_164
	v_lshl_add_u64 v[66:67], v[36:37], 0, s[10:11]
	global_load_dword v65, v[66:67], off nt
.LBB0_164:
	s_or_b64 exec, exec, s[12:13]
	s_waitcnt vmcnt(0)
	ds_write_b32 v6, v65 offset:1056
	s_and_saveexec_b64 s[12:13], vcc
	s_cbranch_execz .LBB0_166
	v_lshl_add_u64 v[66:67], v[34:35], 0, s[10:11]
	global_load_dword v29, v[66:67], off nt
.LBB0_166:
	s_or_b64 exec, exec, s[12:13]
	s_waitcnt vmcnt(0)
	ds_write_b32 v6, v29 offset:1320
	v_mov_b32_e32 v29, 0
	v_mov_b32_e32 v65, 0
	s_and_saveexec_b64 s[12:13], vcc
	s_cbranch_execz .LBB0_168
	v_lshl_add_u64 v[66:67], v[32:33], 0, s[10:11]
	global_load_dword v65, v[66:67], off nt
.LBB0_168:
	s_or_b64 exec, exec, s[12:13]
	s_waitcnt vmcnt(0)
	ds_write_b32 v6, v65 offset:1584
	s_and_saveexec_b64 s[12:13], vcc
	s_cbranch_execz .LBB0_153
	v_lshl_add_u64 v[66:67], v[30:31], 0, s[10:11]
	global_load_dword v29, v[66:67], off nt
	s_branch .LBB0_153
